# main GEMM: first K iteration peeled with zero accumulator inputs on the first-touch MFMAs; the 64 accumulator-zeroing v_mov_b64 per tile removed
# speedup vs baseline: 1.0032x; 1.0032x over previous
.LBB0_1198:
	s_lshl_b32 s52, s1, 8
	s_lshl_b32 s5, s53, 8
	s_add_i32 s0, s5, s62
	s_or_b32 s20, s52, 16
	s_or_b32 s82, s52, 0x80
	s_or_b32 s83, s52, 0x90
	s_add_u32 s84, s8, 0x100
	s_addc_u32 s85, s9, 0
	s_add_u32 s8, s30, 0x80
	s_addc_u32 s9, s31, 0
	s_mov_b32 s86, 0
	s_mov_b64 s[60:61], 0
	s_mov_b64 s[6:7], s[28:29]
.Lkl_first:
	s_add_i32 s87, s86, 2
	s_add_u32 s30, s8, 0x80
	s_addc_u32 s31, s9, 0
	s_add_i32 s88, 16, 0x10000
	s_cmp_eq_u32 s57, s60
	s_cselect_b32 s31, s25, s31
	s_cselect_b32 s30, s24, s30
	v_add_u32_e32 v0, s88, v237
	s_cselect_b32 vcc_hi, s27, s85
	s_cselect_b32 vcc_lo, s26, s84
	s_add_i32 s89, 16, 0x14000
	ds_read_b128 v[132:135], v0
	ds_read_b128 v[136:139], v0 offset:1024
	ds_read_b128 v[152:155], v0 offset:2048
	ds_read_b128 v[156:159], v0 offset:3072
	v_add_u32_e32 v0, s89, v237
	ds_read_b128 v[160:163], v0
	ds_read_b128 v[164:167], v0 offset:1024
	ds_read_b128 v[168:171], v0 offset:2048
	ds_read_b128 v[172:175], v0 offset:3072
	v_lshl_add_u64 v[2:3], s[8:9], 0, v[150:151]
	s_add_i32 m0, s95, 0xc000
	ds_read_b128 v[176:179], v246
	ds_read_b128 v[180:183], v246 offset:1024
	ds_read_b128 v[184:187], v246 offset:2048
	ds_read_b128 v[188:191], v246 offset:3072
	ds_read_b128 v[192:195], v246 offset:4096
	ds_read_b128 v[196:199], v246 offset:5120
	ds_read_b128 v[200:203], v246 offset:6144
	ds_read_b128 v[204:207], v246 offset:7168
	global_load_lds_dwordx4 v[2:3], off
	v_lshl_add_u64 v[2:3], s[8:9], 0, v[148:149]
	s_add_i32 m0, s95, 0xe000
	s_nop 0
	global_load_lds_dwordx4 v[2:3], off
	s_waitcnt vmcnt(8)
	s_waitcnt lgkmcnt(0)
	s_barrier
	s_setprio 1
	s_waitcnt lgkmcnt(0)
	v_mfma_f32_16x16x32_bf16 v[128:131], v[132:135], v[176:179], 0
	v_mfma_f32_16x16x32_bf16 v[124:127], v[152:155], v[176:179], 0
	v_mfma_f32_16x16x32_bf16 v[112:115], v[132:135], v[184:187], 0
	v_mfma_f32_16x16x32_bf16 v[108:111], v[152:155], v[184:187], 0
	v_mfma_f32_16x16x32_bf16 v[96:99], v[132:135], v[192:195], 0
	v_mfma_f32_16x16x32_bf16 v[92:95], v[152:155], v[192:195], 0
	v_mfma_f32_16x16x32_bf16 v[80:83], v[132:135], v[200:203], 0
	v_mfma_f32_16x16x32_bf16 v[76:79], v[152:155], v[200:203], 0
	v_mfma_f32_16x16x32_bf16 v[128:131], v[136:139], v[180:183], v[128:131]
	v_mfma_f32_16x16x32_bf16 v[124:127], v[156:159], v[180:183], v[124:127]
	v_mfma_f32_16x16x32_bf16 v[112:115], v[136:139], v[188:191], v[112:115]
	v_mfma_f32_16x16x32_bf16 v[108:111], v[156:159], v[188:191], v[108:111]
	v_mfma_f32_16x16x32_bf16 v[96:99], v[136:139], v[196:199], v[96:99]
	v_mfma_f32_16x16x32_bf16 v[92:95], v[156:159], v[196:199], v[92:95]
	v_mfma_f32_16x16x32_bf16 v[80:83], v[136:139], v[204:207], v[80:83]
	v_mfma_f32_16x16x32_bf16 v[76:79], v[156:159], v[204:207], v[76:79]
	s_setprio 0
	s_setprio 1
	v_mfma_f32_16x16x32_bf16 v[120:123], v[160:163], v[176:179], 0
	v_mfma_f32_16x16x32_bf16 v[116:119], v[168:171], v[176:179], 0
	v_mfma_f32_16x16x32_bf16 v[104:107], v[160:163], v[184:187], 0
	v_mfma_f32_16x16x32_bf16 v[100:103], v[168:171], v[184:187], 0
	v_mfma_f32_16x16x32_bf16 v[88:91], v[160:163], v[192:195], 0
	v_mfma_f32_16x16x32_bf16 v[84:87], v[168:171], v[192:195], 0
	v_mfma_f32_16x16x32_bf16 v[72:75], v[160:163], v[200:203], 0
	v_mfma_f32_16x16x32_bf16 v[68:71], v[168:171], v[200:203], 0
	v_mfma_f32_16x16x32_bf16 v[120:123], v[164:167], v[180:183], v[120:123]
	v_mfma_f32_16x16x32_bf16 v[116:119], v[172:175], v[180:183], v[116:119]
	v_mfma_f32_16x16x32_bf16 v[104:107], v[164:167], v[188:191], v[104:107]
	v_mfma_f32_16x16x32_bf16 v[100:103], v[172:175], v[188:191], v[100:103]
	v_mfma_f32_16x16x32_bf16 v[88:91], v[164:167], v[196:199], v[88:91]
	v_mfma_f32_16x16x32_bf16 v[84:87], v[172:175], v[196:199], v[84:87]
	v_mfma_f32_16x16x32_bf16 v[72:75], v[164:167], v[204:207], v[72:75]
	v_mfma_f32_16x16x32_bf16 v[68:71], v[172:175], v[204:207], v[68:71]
	s_setprio 0
	s_barrier
	s_add_i32 s88, s88, s93
	v_lshl_add_u64 v[208:209], vcc, 0, v[142:143]
	s_mov_b32 m0, s88
	ds_read_b128 v[176:179], v246 offset:16384
	ds_read_b128 v[180:183], v246 offset:17408
	ds_read_b128 v[184:187], v246 offset:18432
	ds_read_b128 v[188:191], v246 offset:19456
	ds_read_b128 v[192:195], v246 offset:20480
	ds_read_b128 v[196:199], v246 offset:21504
	ds_read_b128 v[200:203], v246 offset:22528
	ds_read_b128 v[204:207], v246 offset:23552
	global_load_lds_dwordx4 v[208:209], off
	s_add_i32 m0, s88, 0x2000
	v_lshl_add_u64 v[210:211], vcc, 0, v[144:145]
	s_add_u32 vcc_lo, vcc_lo, s18
	s_addc_u32 vcc_hi, vcc_hi, 0
	s_add_i32 s88, s89, s93
	global_load_lds_dwordx4 v[210:211], off
	v_lshl_add_u64 v[212:213], vcc, 0, v[142:143]
	s_mov_b32 m0, s88
	v_lshl_add_u64 v[214:215], vcc, 0, v[144:145]
	global_load_lds_dwordx4 v[212:213], off
	s_add_i32 m0, s88, 0x2000
	v_lshl_add_u64 v[224:225], s[30:31], 0, v[142:143]
	global_load_lds_dwordx4 v[214:215], off
	s_mov_b32 m0, s95
	v_lshl_add_u64 v[226:227], s[30:31], 0, v[144:145]
	global_load_lds_dwordx4 v[224:225], off
	s_mov_b32 m0, s96
	s_nop 0
	global_load_lds_dwordx4 v[226:227], off
	s_waitcnt vmcnt(8)
	s_waitcnt lgkmcnt(0)
	s_barrier
	s_setprio 1
	s_waitcnt lgkmcnt(0)
	v_mfma_f32_16x16x32_bf16 v[64:67], v[132:135], v[176:179], 0
	v_mfma_f32_16x16x32_bf16 v[60:63], v[152:155], v[176:179], 0
	v_mfma_f32_16x16x32_bf16 v[48:51], v[132:135], v[184:187], 0
	v_mfma_f32_16x16x32_bf16 v[44:47], v[152:155], v[184:187], 0
	v_mfma_f32_16x16x32_bf16 v[32:35], v[132:135], v[192:195], 0
	v_mfma_f32_16x16x32_bf16 v[28:31], v[152:155], v[192:195], 0
	v_mfma_f32_16x16x32_bf16 v[16:19], v[132:135], v[200:203], 0
	v_mfma_f32_16x16x32_bf16 v[12:15], v[152:155], v[200:203], 0
	v_mfma_f32_16x16x32_bf16 v[64:67], v[136:139], v[180:183], v[64:67]
	v_mfma_f32_16x16x32_bf16 v[60:63], v[156:159], v[180:183], v[60:63]
	v_mfma_f32_16x16x32_bf16 v[48:51], v[136:139], v[188:191], v[48:51]
	v_mfma_f32_16x16x32_bf16 v[44:47], v[156:159], v[188:191], v[44:47]
	v_mfma_f32_16x16x32_bf16 v[32:35], v[136:139], v[196:199], v[32:35]
	v_mfma_f32_16x16x32_bf16 v[28:31], v[156:159], v[196:199], v[28:31]
	v_mfma_f32_16x16x32_bf16 v[16:19], v[136:139], v[204:207], v[16:19]
	v_mfma_f32_16x16x32_bf16 v[12:15], v[156:159], v[204:207], v[12:15]
	s_setprio 0
	s_setprio 1
	v_mfma_f32_16x16x32_bf16 v[56:59], v[160:163], v[176:179], 0
	v_mfma_f32_16x16x32_bf16 v[52:55], v[168:171], v[176:179], 0
	v_mfma_f32_16x16x32_bf16 v[40:43], v[160:163], v[184:187], 0
	v_mfma_f32_16x16x32_bf16 v[36:39], v[168:171], v[184:187], 0
	v_mfma_f32_16x16x32_bf16 v[24:27], v[160:163], v[192:195], 0
	v_mfma_f32_16x16x32_bf16 v[20:23], v[168:171], v[192:195], 0
	v_mfma_f32_16x16x32_bf16 v[8:11], v[160:163], v[200:203], 0
	v_mfma_f32_16x16x32_bf16 v[2:5], v[168:171], v[200:203], 0
	v_mfma_f32_16x16x32_bf16 v[56:59], v[164:167], v[180:183], v[56:59]
	v_mfma_f32_16x16x32_bf16 v[52:55], v[172:175], v[180:183], v[52:55]
	v_mfma_f32_16x16x32_bf16 v[40:43], v[164:167], v[188:191], v[40:43]
	v_mfma_f32_16x16x32_bf16 v[36:39], v[172:175], v[188:191], v[36:39]
	v_mfma_f32_16x16x32_bf16 v[24:27], v[164:167], v[196:199], v[24:27]
	v_mfma_f32_16x16x32_bf16 v[20:23], v[172:175], v[196:199], v[20:23]
	v_mfma_f32_16x16x32_bf16 v[8:11], v[164:167], v[204:207], v[8:11]
	v_mfma_f32_16x16x32_bf16 v[2:5], v[172:175], v[204:207], v[2:5]
	s_setprio 0
	s_barrier
	s_add_i32 s88, 16, 0x18000
	v_add_u32_e32 v0, s88, v237
	s_add_i32 s89, 16, 0x1c000
	ds_read_b128 v[132:135], v0
	ds_read_b128 v[136:139], v0 offset:1024
	ds_read_b128 v[152:155], v0 offset:2048
	ds_read_b128 v[156:159], v0 offset:3072
	v_add_u32_e32 v0, s89, v237
	ds_read_b128 v[160:163], v0
	ds_read_b128 v[164:167], v0 offset:1024
	ds_read_b128 v[168:171], v0 offset:2048
	ds_read_b128 v[172:175], v0 offset:3072
	s_add_u32 s30, s30, s18
	s_addc_u32 s31, s31, 0
	s_mov_b32 m0, s97
	v_lshl_add_u64 v[6:7], s[30:31], 0, v[142:143]
	ds_read_b128 v[176:179], v246 offset:32768
	ds_read_b128 v[180:183], v246 offset:33792
	ds_read_b128 v[184:187], v246 offset:34816
	ds_read_b128 v[188:191], v246 offset:35840
	ds_read_b128 v[192:195], v246 offset:36864
	ds_read_b128 v[196:199], v246 offset:37888
	ds_read_b128 v[200:203], v246 offset:38912
	ds_read_b128 v[204:207], v246 offset:39936
	global_load_lds_dwordx4 v[6:7], off
	v_lshl_add_u64 v[6:7], s[30:31], 0, v[144:145]
	s_mov_b32 m0, s58
	s_nop 0
	global_load_lds_dwordx4 v[6:7], off
	s_waitcnt vmcnt(8)
	s_waitcnt lgkmcnt(0)
	s_barrier
	s_setprio 1
	s_waitcnt lgkmcnt(0)
	v_mfma_f32_16x16x32_bf16 v[128:131], v[132:135], v[176:179], v[128:131]
	v_mfma_f32_16x16x32_bf16 v[124:127], v[152:155], v[176:179], v[124:127]
	v_mfma_f32_16x16x32_bf16 v[112:115], v[132:135], v[184:187], v[112:115]
	v_mfma_f32_16x16x32_bf16 v[108:111], v[152:155], v[184:187], v[108:111]
	v_mfma_f32_16x16x32_bf16 v[96:99], v[132:135], v[192:195], v[96:99]
	v_mfma_f32_16x16x32_bf16 v[92:95], v[152:155], v[192:195], v[92:95]
	v_mfma_f32_16x16x32_bf16 v[80:83], v[132:135], v[200:203], v[80:83]
	v_mfma_f32_16x16x32_bf16 v[76:79], v[152:155], v[200:203], v[76:79]
	v_mfma_f32_16x16x32_bf16 v[128:131], v[136:139], v[180:183], v[128:131]
	v_mfma_f32_16x16x32_bf16 v[124:127], v[156:159], v[180:183], v[124:127]
	v_mfma_f32_16x16x32_bf16 v[112:115], v[136:139], v[188:191], v[112:115]
	v_mfma_f32_16x16x32_bf16 v[108:111], v[156:159], v[188:191], v[108:111]
	v_mfma_f32_16x16x32_bf16 v[96:99], v[136:139], v[196:199], v[96:99]
	v_mfma_f32_16x16x32_bf16 v[92:95], v[156:159], v[196:199], v[92:95]
	v_mfma_f32_16x16x32_bf16 v[80:83], v[136:139], v[204:207], v[80:83]
	v_mfma_f32_16x16x32_bf16 v[76:79], v[156:159], v[204:207], v[76:79]
	s_setprio 0
	s_setprio 1
	v_mfma_f32_16x16x32_bf16 v[120:123], v[160:163], v[176:179], v[120:123]
	v_mfma_f32_16x16x32_bf16 v[116:119], v[168:171], v[176:179], v[116:119]
	v_mfma_f32_16x16x32_bf16 v[104:107], v[160:163], v[184:187], v[104:107]
	v_mfma_f32_16x16x32_bf16 v[100:103], v[168:171], v[184:187], v[100:103]
	v_mfma_f32_16x16x32_bf16 v[88:91], v[160:163], v[192:195], v[88:91]
	v_mfma_f32_16x16x32_bf16 v[84:87], v[168:171], v[192:195], v[84:87]
	v_mfma_f32_16x16x32_bf16 v[72:75], v[160:163], v[200:203], v[72:75]
	v_mfma_f32_16x16x32_bf16 v[68:71], v[168:171], v[200:203], v[68:71]
	v_mfma_f32_16x16x32_bf16 v[120:123], v[164:167], v[180:183], v[120:123]
	v_mfma_f32_16x16x32_bf16 v[116:119], v[172:175], v[180:183], v[116:119]
	v_mfma_f32_16x16x32_bf16 v[104:107], v[164:167], v[188:191], v[104:107]
	v_mfma_f32_16x16x32_bf16 v[100:103], v[172:175], v[188:191], v[100:103]
	v_mfma_f32_16x16x32_bf16 v[88:91], v[164:167], v[196:199], v[88:91]
	v_mfma_f32_16x16x32_bf16 v[84:87], v[172:175], v[196:199], v[84:87]
	v_mfma_f32_16x16x32_bf16 v[72:75], v[164:167], v[204:207], v[72:75]
	v_mfma_f32_16x16x32_bf16 v[68:71], v[172:175], v[204:207], v[68:71]
	s_setprio 0
	s_barrier
	s_add_i32 s30, s88, s93
	v_lshl_add_u64 v[6:7], v[208:209], 0, s[36:37]
	s_mov_b32 m0, s30
	ds_read_b128 v[176:179], v246 offset:49152
	ds_read_b128 v[180:183], v246 offset:50176
	ds_read_b128 v[184:187], v246 offset:51200
	ds_read_b128 v[188:191], v246 offset:52224
	ds_read_b128 v[192:195], v246 offset:53248
	ds_read_b128 v[196:199], v246 offset:54272
	ds_read_b128 v[200:203], v246 offset:55296
	ds_read_b128 v[204:207], v246 offset:56320
	global_load_lds_dwordx4 v[6:7], off
	v_lshl_add_u64 v[6:7], v[210:211], 0, s[36:37]
	s_add_i32 m0, s30, 0x2000
	s_add_i32 s30, s89, s93
	global_load_lds_dwordx4 v[6:7], off
	v_lshl_add_u64 v[6:7], v[212:213], 0, s[36:37]
	s_mov_b32 m0, s30
	s_nop 0
	global_load_lds_dwordx4 v[6:7], off
	v_lshl_add_u64 v[6:7], v[214:215], 0, s[36:37]
	s_add_i32 m0, s30, 0x2000
	s_nop 0
	global_load_lds_dwordx4 v[6:7], off
	v_lshl_add_u64 v[6:7], v[224:225], 0, s[36:37]
	s_mov_b32 m0, s21
	s_nop 0
	global_load_lds_dwordx4 v[6:7], off
	v_lshl_add_u64 v[6:7], v[226:227], 0, s[36:37]
	s_mov_b32 m0, s33
	s_nop 0
	global_load_lds_dwordx4 v[6:7], off
	s_waitcnt vmcnt(8)
	s_waitcnt lgkmcnt(0)
	s_barrier
	s_setprio 1
	s_waitcnt lgkmcnt(0)
	v_mfma_f32_16x16x32_bf16 v[64:67], v[132:135], v[176:179], v[64:67]
	v_mfma_f32_16x16x32_bf16 v[60:63], v[152:155], v[176:179], v[60:63]
	v_mfma_f32_16x16x32_bf16 v[48:51], v[132:135], v[184:187], v[48:51]
	v_mfma_f32_16x16x32_bf16 v[44:47], v[152:155], v[184:187], v[44:47]
	v_mfma_f32_16x16x32_bf16 v[32:35], v[132:135], v[192:195], v[32:35]
	v_mfma_f32_16x16x32_bf16 v[28:31], v[152:155], v[192:195], v[28:31]
	v_mfma_f32_16x16x32_bf16 v[16:19], v[132:135], v[200:203], v[16:19]
	v_mfma_f32_16x16x32_bf16 v[12:15], v[152:155], v[200:203], v[12:15]
	v_mfma_f32_16x16x32_bf16 v[64:67], v[136:139], v[180:183], v[64:67]
	v_mfma_f32_16x16x32_bf16 v[60:63], v[156:159], v[180:183], v[60:63]
	v_mfma_f32_16x16x32_bf16 v[48:51], v[136:139], v[188:191], v[48:51]
	v_mfma_f32_16x16x32_bf16 v[44:47], v[156:159], v[188:191], v[44:47]
	v_mfma_f32_16x16x32_bf16 v[32:35], v[136:139], v[196:199], v[32:35]
	v_mfma_f32_16x16x32_bf16 v[28:31], v[156:159], v[196:199], v[28:31]
	v_mfma_f32_16x16x32_bf16 v[16:19], v[136:139], v[204:207], v[16:19]
	v_mfma_f32_16x16x32_bf16 v[12:15], v[156:159], v[204:207], v[12:15]
	s_setprio 0
	s_setprio 1
	v_mfma_f32_16x16x32_bf16 v[56:59], v[160:163], v[176:179], v[56:59]
	v_mfma_f32_16x16x32_bf16 v[52:55], v[168:171], v[176:179], v[52:55]
	v_mfma_f32_16x16x32_bf16 v[40:43], v[160:163], v[184:187], v[40:43]
	v_mfma_f32_16x16x32_bf16 v[36:39], v[168:171], v[184:187], v[36:39]
	v_mfma_f32_16x16x32_bf16 v[24:27], v[160:163], v[192:195], v[24:27]
	v_mfma_f32_16x16x32_bf16 v[20:23], v[168:171], v[192:195], v[20:23]
	v_mfma_f32_16x16x32_bf16 v[6:9], v[160:163], v[200:203], v[8:11]
	v_mfma_f32_16x16x32_bf16 v[2:5], v[168:171], v[200:203], v[2:5]
	v_mfma_f32_16x16x32_bf16 v[56:59], v[164:167], v[180:183], v[56:59]
	v_mfma_f32_16x16x32_bf16 v[52:55], v[172:175], v[180:183], v[52:55]
	v_mfma_f32_16x16x32_bf16 v[40:43], v[164:167], v[188:191], v[40:43]
	v_mfma_f32_16x16x32_bf16 v[36:39], v[172:175], v[188:191], v[36:39]
	v_mfma_f32_16x16x32_bf16 v[24:27], v[164:167], v[196:199], v[24:27]
	v_mfma_f32_16x16x32_bf16 v[20:23], v[172:175], v[196:199], v[20:23]
	v_mfma_f32_16x16x32_bf16 v[8:11], v[164:167], v[204:207], v[6:9]
	v_mfma_f32_16x16x32_bf16 v[4:7], v[172:175], v[204:207], v[2:5]
	s_setprio 0
	s_barrier
	s_andn2_b64 vcc, exec, s[22:23]
	s_cbranch_vccnz .LBB0_1202
	s_branch .Lkl_1200
.LBB0_1199:
	s_add_i32 s87, s86, 2
	s_add_u32 s30, s8, 0x80
	s_addc_u32 s31, s9, 0
	s_add_i32 s88, 16, 0x10000
	s_cmp_eq_u32 s57, s60
	s_cselect_b32 s31, s25, s31
	s_cselect_b32 s30, s24, s30
	v_add_u32_e32 v0, s88, v237
	s_cselect_b32 vcc_hi, s27, s85
	s_cselect_b32 vcc_lo, s26, s84
	s_add_i32 s89, 16, 0x14000
	ds_read_b128 v[132:135], v0
	ds_read_b128 v[136:139], v0 offset:1024
	ds_read_b128 v[152:155], v0 offset:2048
	ds_read_b128 v[156:159], v0 offset:3072
	v_add_u32_e32 v0, s89, v237
	ds_read_b128 v[160:163], v0
	ds_read_b128 v[164:167], v0 offset:1024
	ds_read_b128 v[168:171], v0 offset:2048
	ds_read_b128 v[172:175], v0 offset:3072
	v_lshl_add_u64 v[2:3], s[8:9], 0, v[150:151]
	s_add_i32 m0, s95, 0xc000
	ds_read_b128 v[176:179], v246
	ds_read_b128 v[180:183], v246 offset:1024
	ds_read_b128 v[184:187], v246 offset:2048
	ds_read_b128 v[188:191], v246 offset:3072
	ds_read_b128 v[192:195], v246 offset:4096
	ds_read_b128 v[196:199], v246 offset:5120
	ds_read_b128 v[200:203], v246 offset:6144
	ds_read_b128 v[204:207], v246 offset:7168
	global_load_lds_dwordx4 v[2:3], off
	v_lshl_add_u64 v[2:3], s[8:9], 0, v[148:149]
	s_add_i32 m0, s95, 0xe000
	s_nop 0
	global_load_lds_dwordx4 v[2:3], off
	s_waitcnt vmcnt(8)
	s_waitcnt lgkmcnt(0)
	s_barrier
	s_setprio 1
	s_waitcnt lgkmcnt(0)
	v_mfma_f32_16x16x32_bf16 v[128:131], v[132:135], v[176:179], v[128:131]
	v_mfma_f32_16x16x32_bf16 v[124:127], v[152:155], v[176:179], v[124:127]
	v_mfma_f32_16x16x32_bf16 v[112:115], v[132:135], v[184:187], v[112:115]
	v_mfma_f32_16x16x32_bf16 v[108:111], v[152:155], v[184:187], v[108:111]
	v_mfma_f32_16x16x32_bf16 v[96:99], v[132:135], v[192:195], v[96:99]
	v_mfma_f32_16x16x32_bf16 v[92:95], v[152:155], v[192:195], v[92:95]
	v_mfma_f32_16x16x32_bf16 v[80:83], v[132:135], v[200:203], v[80:83]
	v_mfma_f32_16x16x32_bf16 v[76:79], v[152:155], v[200:203], v[76:79]
	v_mfma_f32_16x16x32_bf16 v[128:131], v[136:139], v[180:183], v[128:131]
	v_mfma_f32_16x16x32_bf16 v[124:127], v[156:159], v[180:183], v[124:127]
	v_mfma_f32_16x16x32_bf16 v[112:115], v[136:139], v[188:191], v[112:115]
	v_mfma_f32_16x16x32_bf16 v[108:111], v[156:159], v[188:191], v[108:111]
	v_mfma_f32_16x16x32_bf16 v[96:99], v[136:139], v[196:199], v[96:99]
	v_mfma_f32_16x16x32_bf16 v[92:95], v[156:159], v[196:199], v[92:95]
	v_mfma_f32_16x16x32_bf16 v[80:83], v[136:139], v[204:207], v[80:83]
	v_mfma_f32_16x16x32_bf16 v[76:79], v[156:159], v[204:207], v[76:79]
	s_setprio 0
	s_setprio 1
	v_mfma_f32_16x16x32_bf16 v[120:123], v[160:163], v[176:179], v[120:123]
	v_mfma_f32_16x16x32_bf16 v[116:119], v[168:171], v[176:179], v[116:119]
	v_mfma_f32_16x16x32_bf16 v[104:107], v[160:163], v[184:187], v[104:107]
	v_mfma_f32_16x16x32_bf16 v[100:103], v[168:171], v[184:187], v[100:103]
	v_mfma_f32_16x16x32_bf16 v[88:91], v[160:163], v[192:195], v[88:91]
	v_mfma_f32_16x16x32_bf16 v[84:87], v[168:171], v[192:195], v[84:87]
	v_mfma_f32_16x16x32_bf16 v[72:75], v[160:163], v[200:203], v[72:75]
	v_mfma_f32_16x16x32_bf16 v[68:71], v[168:171], v[200:203], v[68:71]
	v_mfma_f32_16x16x32_bf16 v[120:123], v[164:167], v[180:183], v[120:123]
	v_mfma_f32_16x16x32_bf16 v[116:119], v[172:175], v[180:183], v[116:119]
	v_mfma_f32_16x16x32_bf16 v[104:107], v[164:167], v[188:191], v[104:107]
	v_mfma_f32_16x16x32_bf16 v[100:103], v[172:175], v[188:191], v[100:103]
	v_mfma_f32_16x16x32_bf16 v[88:91], v[164:167], v[196:199], v[88:91]
	v_mfma_f32_16x16x32_bf16 v[84:87], v[172:175], v[196:199], v[84:87]
	v_mfma_f32_16x16x32_bf16 v[72:75], v[164:167], v[204:207], v[72:75]
	v_mfma_f32_16x16x32_bf16 v[68:71], v[172:175], v[204:207], v[68:71]
	s_setprio 0
	s_barrier
	s_add_i32 s88, s88, s93
	v_lshl_add_u64 v[208:209], vcc, 0, v[142:143]
	s_mov_b32 m0, s88
	ds_read_b128 v[176:179], v246 offset:16384
	ds_read_b128 v[180:183], v246 offset:17408
	ds_read_b128 v[184:187], v246 offset:18432
	ds_read_b128 v[188:191], v246 offset:19456
	ds_read_b128 v[192:195], v246 offset:20480
	ds_read_b128 v[196:199], v246 offset:21504
	ds_read_b128 v[200:203], v246 offset:22528
	ds_read_b128 v[204:207], v246 offset:23552
	global_load_lds_dwordx4 v[208:209], off
	s_add_i32 m0, s88, 0x2000
	v_lshl_add_u64 v[210:211], vcc, 0, v[144:145]
	s_add_u32 vcc_lo, vcc_lo, s18
	s_addc_u32 vcc_hi, vcc_hi, 0
	s_add_i32 s88, s89, s93
	global_load_lds_dwordx4 v[210:211], off
	v_lshl_add_u64 v[212:213], vcc, 0, v[142:143]
	s_mov_b32 m0, s88
	v_lshl_add_u64 v[214:215], vcc, 0, v[144:145]
	global_load_lds_dwordx4 v[212:213], off
	s_add_i32 m0, s88, 0x2000
	v_lshl_add_u64 v[224:225], s[30:31], 0, v[142:143]
	global_load_lds_dwordx4 v[214:215], off
	s_mov_b32 m0, s95
	v_lshl_add_u64 v[226:227], s[30:31], 0, v[144:145]
	global_load_lds_dwordx4 v[224:225], off
	s_mov_b32 m0, s96
	s_nop 0
	global_load_lds_dwordx4 v[226:227], off
	s_waitcnt vmcnt(8)
	s_waitcnt lgkmcnt(0)
	s_barrier
	s_setprio 1
	s_waitcnt lgkmcnt(0)
	v_mfma_f32_16x16x32_bf16 v[64:67], v[132:135], v[176:179], v[64:67]
	v_mfma_f32_16x16x32_bf16 v[60:63], v[152:155], v[176:179], v[60:63]
	v_mfma_f32_16x16x32_bf16 v[48:51], v[132:135], v[184:187], v[48:51]
	v_mfma_f32_16x16x32_bf16 v[44:47], v[152:155], v[184:187], v[44:47]
	v_mfma_f32_16x16x32_bf16 v[32:35], v[132:135], v[192:195], v[32:35]
	v_mfma_f32_16x16x32_bf16 v[28:31], v[152:155], v[192:195], v[28:31]
	v_mfma_f32_16x16x32_bf16 v[16:19], v[132:135], v[200:203], v[16:19]
	v_mfma_f32_16x16x32_bf16 v[12:15], v[152:155], v[200:203], v[12:15]
	v_mfma_f32_16x16x32_bf16 v[64:67], v[136:139], v[180:183], v[64:67]
	v_mfma_f32_16x16x32_bf16 v[60:63], v[156:159], v[180:183], v[60:63]
	v_mfma_f32_16x16x32_bf16 v[48:51], v[136:139], v[188:191], v[48:51]
	v_mfma_f32_16x16x32_bf16 v[44:47], v[156:159], v[188:191], v[44:47]
	v_mfma_f32_16x16x32_bf16 v[32:35], v[136:139], v[196:199], v[32:35]
	v_mfma_f32_16x16x32_bf16 v[28:31], v[156:159], v[196:199], v[28:31]
	v_mfma_f32_16x16x32_bf16 v[16:19], v[136:139], v[204:207], v[16:19]
	v_mfma_f32_16x16x32_bf16 v[12:15], v[156:159], v[204:207], v[12:15]
	s_setprio 0
	s_setprio 1
	v_mfma_f32_16x16x32_bf16 v[56:59], v[160:163], v[176:179], v[56:59]
	v_mfma_f32_16x16x32_bf16 v[52:55], v[168:171], v[176:179], v[52:55]
	v_mfma_f32_16x16x32_bf16 v[40:43], v[160:163], v[184:187], v[40:43]
	v_mfma_f32_16x16x32_bf16 v[36:39], v[168:171], v[184:187], v[36:39]
	v_mfma_f32_16x16x32_bf16 v[24:27], v[160:163], v[192:195], v[24:27]
	v_mfma_f32_16x16x32_bf16 v[20:23], v[168:171], v[192:195], v[20:23]
	v_mfma_f32_16x16x32_bf16 v[8:11], v[160:163], v[200:203], v[8:11]
	v_mfma_f32_16x16x32_bf16 v[2:5], v[168:171], v[200:203], v[4:7]
	v_mfma_f32_16x16x32_bf16 v[56:59], v[164:167], v[180:183], v[56:59]
	v_mfma_f32_16x16x32_bf16 v[52:55], v[172:175], v[180:183], v[52:55]
	v_mfma_f32_16x16x32_bf16 v[40:43], v[164:167], v[188:191], v[40:43]
	v_mfma_f32_16x16x32_bf16 v[36:39], v[172:175], v[188:191], v[36:39]
	v_mfma_f32_16x16x32_bf16 v[24:27], v[164:167], v[196:199], v[24:27]
	v_mfma_f32_16x16x32_bf16 v[20:23], v[172:175], v[196:199], v[20:23]
	v_mfma_f32_16x16x32_bf16 v[8:11], v[164:167], v[204:207], v[8:11]
	v_mfma_f32_16x16x32_bf16 v[2:5], v[172:175], v[204:207], v[2:5]
	s_setprio 0
	s_barrier
	s_add_i32 s88, 16, 0x18000
	v_add_u32_e32 v0, s88, v237
	s_add_i32 s89, 16, 0x1c000
	ds_read_b128 v[132:135], v0
	ds_read_b128 v[136:139], v0 offset:1024
	ds_read_b128 v[152:155], v0 offset:2048
	ds_read_b128 v[156:159], v0 offset:3072
	v_add_u32_e32 v0, s89, v237
	ds_read_b128 v[160:163], v0
	ds_read_b128 v[164:167], v0 offset:1024
	ds_read_b128 v[168:171], v0 offset:2048
	ds_read_b128 v[172:175], v0 offset:3072
	s_add_u32 s30, s30, s18
	s_addc_u32 s31, s31, 0
	s_mov_b32 m0, s97
	v_lshl_add_u64 v[6:7], s[30:31], 0, v[142:143]
	ds_read_b128 v[176:179], v246 offset:32768
	ds_read_b128 v[180:183], v246 offset:33792
	ds_read_b128 v[184:187], v246 offset:34816
	ds_read_b128 v[188:191], v246 offset:35840
	ds_read_b128 v[192:195], v246 offset:36864
	ds_read_b128 v[196:199], v246 offset:37888
	ds_read_b128 v[200:203], v246 offset:38912
	ds_read_b128 v[204:207], v246 offset:39936
	global_load_lds_dwordx4 v[6:7], off
	v_lshl_add_u64 v[6:7], s[30:31], 0, v[144:145]
	s_mov_b32 m0, s58
	s_nop 0
	global_load_lds_dwordx4 v[6:7], off
	s_waitcnt vmcnt(8)
	s_waitcnt lgkmcnt(0)
	s_barrier
	s_setprio 1
	s_waitcnt lgkmcnt(0)
	v_mfma_f32_16x16x32_bf16 v[128:131], v[132:135], v[176:179], v[128:131]
	v_mfma_f32_16x16x32_bf16 v[124:127], v[152:155], v[176:179], v[124:127]
	v_mfma_f32_16x16x32_bf16 v[112:115], v[132:135], v[184:187], v[112:115]
	v_mfma_f32_16x16x32_bf16 v[108:111], v[152:155], v[184:187], v[108:111]
	v_mfma_f32_16x16x32_bf16 v[96:99], v[132:135], v[192:195], v[96:99]
	v_mfma_f32_16x16x32_bf16 v[92:95], v[152:155], v[192:195], v[92:95]
	v_mfma_f32_16x16x32_bf16 v[80:83], v[132:135], v[200:203], v[80:83]
	v_mfma_f32_16x16x32_bf16 v[76:79], v[152:155], v[200:203], v[76:79]
	v_mfma_f32_16x16x32_bf16 v[128:131], v[136:139], v[180:183], v[128:131]
	v_mfma_f32_16x16x32_bf16 v[124:127], v[156:159], v[180:183], v[124:127]
	v_mfma_f32_16x16x32_bf16 v[112:115], v[136:139], v[188:191], v[112:115]
	v_mfma_f32_16x16x32_bf16 v[108:111], v[156:159], v[188:191], v[108:111]
	v_mfma_f32_16x16x32_bf16 v[96:99], v[136:139], v[196:199], v[96:99]
	v_mfma_f32_16x16x32_bf16 v[92:95], v[156:159], v[196:199], v[92:95]
	v_mfma_f32_16x16x32_bf16 v[80:83], v[136:139], v[204:207], v[80:83]
	v_mfma_f32_16x16x32_bf16 v[76:79], v[156:159], v[204:207], v[76:79]
	s_setprio 0
	s_setprio 1
	v_mfma_f32_16x16x32_bf16 v[120:123], v[160:163], v[176:179], v[120:123]
	v_mfma_f32_16x16x32_bf16 v[116:119], v[168:171], v[176:179], v[116:119]
	v_mfma_f32_16x16x32_bf16 v[104:107], v[160:163], v[184:187], v[104:107]
	v_mfma_f32_16x16x32_bf16 v[100:103], v[168:171], v[184:187], v[100:103]
	v_mfma_f32_16x16x32_bf16 v[88:91], v[160:163], v[192:195], v[88:91]
	v_mfma_f32_16x16x32_bf16 v[84:87], v[168:171], v[192:195], v[84:87]
	v_mfma_f32_16x16x32_bf16 v[72:75], v[160:163], v[200:203], v[72:75]
	v_mfma_f32_16x16x32_bf16 v[68:71], v[168:171], v[200:203], v[68:71]
	v_mfma_f32_16x16x32_bf16 v[120:123], v[164:167], v[180:183], v[120:123]
	v_mfma_f32_16x16x32_bf16 v[116:119], v[172:175], v[180:183], v[116:119]
	v_mfma_f32_16x16x32_bf16 v[104:107], v[164:167], v[188:191], v[104:107]
	v_mfma_f32_16x16x32_bf16 v[100:103], v[172:175], v[188:191], v[100:103]
	v_mfma_f32_16x16x32_bf16 v[88:91], v[164:167], v[196:199], v[88:91]
	v_mfma_f32_16x16x32_bf16 v[84:87], v[172:175], v[196:199], v[84:87]
	v_mfma_f32_16x16x32_bf16 v[72:75], v[164:167], v[204:207], v[72:75]
	v_mfma_f32_16x16x32_bf16 v[68:71], v[172:175], v[204:207], v[68:71]
	s_setprio 0
	s_barrier
	s_add_i32 s30, s88, s93
	v_lshl_add_u64 v[6:7], v[208:209], 0, s[36:37]
	s_mov_b32 m0, s30
	ds_read_b128 v[176:179], v246 offset:49152
	ds_read_b128 v[180:183], v246 offset:50176
	ds_read_b128 v[184:187], v246 offset:51200
	ds_read_b128 v[188:191], v246 offset:52224
	ds_read_b128 v[192:195], v246 offset:53248
	ds_read_b128 v[196:199], v246 offset:54272
	ds_read_b128 v[200:203], v246 offset:55296
	ds_read_b128 v[204:207], v246 offset:56320
	global_load_lds_dwordx4 v[6:7], off
	v_lshl_add_u64 v[6:7], v[210:211], 0, s[36:37]
	s_add_i32 m0, s30, 0x2000
	s_add_i32 s30, s89, s93
	global_load_lds_dwordx4 v[6:7], off
	v_lshl_add_u64 v[6:7], v[212:213], 0, s[36:37]
	s_mov_b32 m0, s30
	s_nop 0
	global_load_lds_dwordx4 v[6:7], off
	v_lshl_add_u64 v[6:7], v[214:215], 0, s[36:37]
	s_add_i32 m0, s30, 0x2000
	s_nop 0
	global_load_lds_dwordx4 v[6:7], off
	v_lshl_add_u64 v[6:7], v[224:225], 0, s[36:37]
	s_mov_b32 m0, s21
	s_nop 0
	global_load_lds_dwordx4 v[6:7], off
	v_lshl_add_u64 v[6:7], v[226:227], 0, s[36:37]
	s_mov_b32 m0, s33
	s_nop 0
	global_load_lds_dwordx4 v[6:7], off
	s_waitcnt vmcnt(8)
	s_waitcnt lgkmcnt(0)
	s_barrier
	s_setprio 1
	s_waitcnt lgkmcnt(0)
	v_mfma_f32_16x16x32_bf16 v[64:67], v[132:135], v[176:179], v[64:67]
	v_mfma_f32_16x16x32_bf16 v[60:63], v[152:155], v[176:179], v[60:63]
	v_mfma_f32_16x16x32_bf16 v[48:51], v[132:135], v[184:187], v[48:51]
	v_mfma_f32_16x16x32_bf16 v[44:47], v[152:155], v[184:187], v[44:47]
	v_mfma_f32_16x16x32_bf16 v[32:35], v[132:135], v[192:195], v[32:35]
	v_mfma_f32_16x16x32_bf16 v[28:31], v[152:155], v[192:195], v[28:31]
	v_mfma_f32_16x16x32_bf16 v[16:19], v[132:135], v[200:203], v[16:19]
	v_mfma_f32_16x16x32_bf16 v[12:15], v[152:155], v[200:203], v[12:15]
	v_mfma_f32_16x16x32_bf16 v[64:67], v[136:139], v[180:183], v[64:67]
	v_mfma_f32_16x16x32_bf16 v[60:63], v[156:159], v[180:183], v[60:63]
	v_mfma_f32_16x16x32_bf16 v[48:51], v[136:139], v[188:191], v[48:51]
	v_mfma_f32_16x16x32_bf16 v[44:47], v[156:159], v[188:191], v[44:47]
	v_mfma_f32_16x16x32_bf16 v[32:35], v[136:139], v[196:199], v[32:35]
	v_mfma_f32_16x16x32_bf16 v[28:31], v[156:159], v[196:199], v[28:31]
	v_mfma_f32_16x16x32_bf16 v[16:19], v[136:139], v[204:207], v[16:19]
	v_mfma_f32_16x16x32_bf16 v[12:15], v[156:159], v[204:207], v[12:15]
	s_setprio 0
	s_setprio 1
	v_mfma_f32_16x16x32_bf16 v[56:59], v[160:163], v[176:179], v[56:59]
	v_mfma_f32_16x16x32_bf16 v[52:55], v[168:171], v[176:179], v[52:55]
	v_mfma_f32_16x16x32_bf16 v[40:43], v[160:163], v[184:187], v[40:43]
	v_mfma_f32_16x16x32_bf16 v[36:39], v[168:171], v[184:187], v[36:39]
	v_mfma_f32_16x16x32_bf16 v[24:27], v[160:163], v[192:195], v[24:27]
	v_mfma_f32_16x16x32_bf16 v[20:23], v[168:171], v[192:195], v[20:23]
	v_mfma_f32_16x16x32_bf16 v[6:9], v[160:163], v[200:203], v[8:11]
	v_mfma_f32_16x16x32_bf16 v[2:5], v[168:171], v[200:203], v[2:5]
	v_mfma_f32_16x16x32_bf16 v[56:59], v[164:167], v[180:183], v[56:59]
	v_mfma_f32_16x16x32_bf16 v[52:55], v[172:175], v[180:183], v[52:55]
	v_mfma_f32_16x16x32_bf16 v[40:43], v[164:167], v[188:191], v[40:43]
	v_mfma_f32_16x16x32_bf16 v[36:39], v[172:175], v[188:191], v[36:39]
	v_mfma_f32_16x16x32_bf16 v[24:27], v[164:167], v[196:199], v[24:27]
	v_mfma_f32_16x16x32_bf16 v[20:23], v[172:175], v[196:199], v[20:23]
	v_mfma_f32_16x16x32_bf16 v[8:11], v[164:167], v[204:207], v[6:9]
	v_mfma_f32_16x16x32_bf16 v[4:7], v[172:175], v[204:207], v[2:5]
	s_setprio 0
	s_barrier
	s_andn2_b64 vcc, exec, s[22:23]
	s_cbranch_vccnz .LBB0_1202
.Lkl_1200:
	s_bitcmp1_b32 s86, 1
	s_cselect_b64 s[30:31], -1, 0
	s_cmp_lt_u32 s87, s56
	s_cselect_b64 vcc, -1, 0
	s_and_b64 s[30:31], s[30:31], vcc
	s_andn2_b64 vcc, exec, s[30:31]
	s_cbranch_vccnz .LBB0_1202
	v_mov_b32_e32 v140, v234
	v_mov_b32_e32 v0, v235
	s_nop 0
	v_lshl_add_u32 v0, v0, 2, s4
	v_add_u32_e32 v2, s52, v0
	v_ashrrev_i32_e32 v3, 31, v2
	v_lshl_add_u64 v[136:137], v[2:3], 2, s[6:7]
	v_add_u32_e32 v174, s0, v140
	v_lshlrev_b64 v[2:3], 1, v[2:3]
	v_mad_i64_i32 v[152:153], s[30:31], v174, s2, v[2:3]
	s_add_u32 s30, s10, s60
	s_addc_u32 s31, s11, s61
	v_lshl_add_u64 v[152:153], s[30:31], 0, v[152:153]
	v_add_co_u32_e32 v154, vcc, s76, v152
	v_add_u32_e32 v175, 16, v174
	s_nop 0
	v_addc_co_u32_e32 v155, vcc, 0, v153, vcc
	v_add_co_u32_e32 v152, vcc, s77, v152
	global_load_dwordx4 v[132:135], v[136:137], off offset:-4096
	s_nop 0
	global_load_dwordx4 v[136:139], v[136:137], off
	v_addc_co_u32_e32 v153, vcc, 0, v153, vcc
	v_mad_i64_i32 v[156:157], vcc, v175, s2, v[2:3]
	v_lshl_add_u64 v[156:157], s[30:31], 0, v[156:157]
	v_add_co_u32_e32 v158, vcc, s76, v156
	v_add_u32_e32 v176, 32, v174
	s_nop 0
	v_addc_co_u32_e32 v159, vcc, 0, v157, vcc
	v_add_co_u32_e32 v156, vcc, s77, v156
	v_add_u32_e32 v177, 48, v174
	s_nop 0
	v_addc_co_u32_e32 v157, vcc, 0, v157, vcc
	global_load_dwordx2 v[182:183], v[154:155], off offset:3072
	global_load_dwordx2 v[184:185], v[152:153], off offset:1024
	global_load_dwordx2 v[186:187], v[158:159], off offset:3072
	global_load_dwordx2 v[188:189], v[156:157], off offset:1024
	v_mad_i64_i32 v[152:153], vcc, v176, s2, v[2:3]
	v_lshl_add_u64 v[152:153], s[30:31], 0, v[152:153]
	v_add_co_u32_e32 v154, vcc, s76, v152
	v_add_u32_e32 v178, 0x80, v174
	s_nop 0
	v_addc_co_u32_e32 v155, vcc, 0, v153, vcc
	v_add_co_u32_e32 v152, vcc, s77, v152
	v_add_u32_e32 v179, 0x90, v174
	s_nop 0
	v_addc_co_u32_e32 v153, vcc, 0, v153, vcc
	v_mad_i64_i32 v[156:157], vcc, v177, s2, v[2:3]
	v_lshl_add_u64 v[156:157], s[30:31], 0, v[156:157]
	v_add_co_u32_e32 v158, vcc, s76, v156
	v_add_u32_e32 v180, 0xa0, v174
	s_nop 0
	v_addc_co_u32_e32 v159, vcc, 0, v157, vcc
	v_add_co_u32_e32 v156, vcc, s77, v156
	v_add_u32_e32 v181, 0xb0, v174
	s_nop 0
	v_addc_co_u32_e32 v157, vcc, 0, v157, vcc
	global_load_dwordx2 v[170:171], v[154:155], off offset:3072
	global_load_dwordx2 v[172:173], v[152:153], off offset:1024
	global_load_dwordx2 v[166:167], v[158:159], off offset:3072
	global_load_dwordx2 v[168:169], v[156:157], off offset:1024
	v_mad_i64_i32 v[152:153], vcc, v178, s2, v[2:3]
	v_lshl_add_u64 v[152:153], s[30:31], 0, v[152:153]
	v_add_co_u32_e32 v154, vcc, s76, v152
	s_nop 1
	v_addc_co_u32_e32 v155, vcc, 0, v153, vcc
	v_add_co_u32_e32 v152, vcc, s77, v152
	s_nop 1
	v_addc_co_u32_e32 v153, vcc, 0, v153, vcc
	v_mad_i64_i32 v[156:157], vcc, v179, s2, v[2:3]
	v_lshl_add_u64 v[156:157], s[30:31], 0, v[156:157]
	v_add_co_u32_e32 v158, vcc, s76, v156
	s_nop 1
	v_addc_co_u32_e32 v159, vcc, 0, v157, vcc
	v_add_co_u32_e32 v156, vcc, s77, v156
	s_nop 1
	v_addc_co_u32_e32 v157, vcc, 0, v157, vcc
	global_load_dwordx2 v[162:163], v[154:155], off offset:3072
	global_load_dwordx2 v[164:165], v[152:153], off offset:1024
	s_nop 0
	global_load_dwordx2 v[158:159], v[158:159], off offset:3072
	s_nop 0
	global_load_dwordx2 v[160:161], v[156:157], off offset:1024
	v_mad_i64_i32 v[152:153], vcc, v180, s2, v[2:3]
	v_lshl_add_u64 v[152:153], s[30:31], 0, v[152:153]
	v_add_co_u32_e32 v154, vcc, s76, v152
	s_nop 1
	v_addc_co_u32_e32 v155, vcc, 0, v153, vcc
	v_add_co_u32_e32 v152, vcc, s77, v152
	s_nop 1
	v_addc_co_u32_e32 v153, vcc, 0, v153, vcc
	v_mad_i64_i32 v[2:3], vcc, v181, s2, v[2:3]
	v_lshl_add_u64 v[2:3], s[30:31], 0, v[2:3]
	v_add_co_u32_e32 v190, vcc, s76, v2
	s_nop 1
	v_addc_co_u32_e32 v191, vcc, 0, v3, vcc
	v_add_co_u32_e32 v192, vcc, s77, v2
	s_waitcnt vmcnt(0)
	v_lshlrev_b32_e32 v2, 16, v184
	v_add_f32_e32 v2, v136, v2
	v_mul_f32_e32 v2, 0xbfb8aa3b, v2
	v_exp_f32_e32 v140, v2
	v_lshlrev_b32_e32 v2, 16, v182
	v_add_f32_e32 v2, v132, v2
	v_mul_f32_e32 v2, 0xbfb8aa3b, v2
	v_exp_f32_e32 v141, v2
	v_addc_co_u32_e32 v193, vcc, 0, v3, vcc
	global_load_dwordx2 v[154:155], v[154:155], off offset:3072
	s_nop 0
	global_load_dwordx2 v[156:157], v[152:153], off offset:1024
	global_load_dwordx2 v[2:3], v[190:191], off offset:3072
	s_nop 0
	global_load_dwordx2 v[152:153], v[192:193], off offset:1024
	v_min_f32_e32 v190, 0x60ad78ec, v140
	v_min_f32_e32 v140, 0x60ad78ec, v141
	v_and_b32_e32 v141, 0xffff0000, v184
	v_add_f32_e32 v141, v137, v141
	v_mul_f32_e32 v141, 0xbfb8aa3b, v141
	v_exp_f32_e32 v141, v141
	v_and_b32_e32 v182, 0xffff0000, v182
	v_add_f32_e32 v182, v133, v182
	v_mul_f32_e32 v182, 0xbfb8aa3b, v182
	v_exp_f32_e32 v182, v182
	v_min_f32_e32 v191, 0x60ad78ec, v141
	v_lshlrev_b32_e32 v141, 16, v185
	v_add_f32_e32 v141, v138, v141
	v_add_f32_e32 v140, 1.0, v140
	v_mul_f32_e32 v141, 0xbfb8aa3b, v141
	v_rcp_f32_e32 v192, v140
	v_min_f32_e32 v140, 0x60ad78ec, v182
	v_exp_f32_e32 v141, v141
	v_lshlrev_b32_e32 v182, 16, v183
	v_add_f32_e32 v182, v134, v182
	v_mul_f32_e32 v182, 0xbfb8aa3b, v182
	v_and_b32_e32 v183, 0xffff0000, v183
	v_exp_f32_e32 v184, v182
	v_add_f32_e32 v183, v135, v183
	v_min_f32_e32 v182, 0x60ad78ec, v141
	v_and_b32_e32 v141, 0xffff0000, v185
	v_mul_f32_e32 v183, 0xbfb8aa3b, v183
	v_add_f32_e32 v141, v139, v141
	v_exp_f32_e32 v185, v183
	v_add_f32_e32 v140, 1.0, v140
	v_mul_f32_e32 v141, 0xbfb8aa3b, v141
	v_rcp_f32_e32 v193, v140
	v_min_f32_e32 v140, 0x60ad78ec, v184
	v_exp_f32_e32 v141, v141
	v_add_f32_e32 v140, 1.0, v140
	v_rcp_f32_e32 v184, v140
	v_min_f32_e32 v140, 0x60ad78ec, v185
	v_add_f32_e32 v140, 1.0, v140
	v_min_f32_e32 v183, 0x60ad78ec, v141
	v_rcp_f32_e32 v185, v140
	v_lshlrev_b32_e32 v140, 16, v188
	v_lshlrev_b32_e32 v141, 16, v186
	v_add_f32_e32 v140, v136, v140
	v_add_f32_e32 v141, v132, v141
	v_mul_f32_e32 v140, 0xbfb8aa3b, v140
	v_mul_f32_e32 v141, 0xbfb8aa3b, v141
	v_exp_f32_e32 v140, v140
	v_exp_f32_e32 v141, v141
	v_pk_add_f32 v[182:183], v[182:183], 1.0 op_sel_hi:[1,0]
	v_pk_add_f32 v[190:191], v[190:191], 1.0 op_sel_hi:[1,0]
	v_pk_mul_f32 v[182:183], v[182:183], v[184:185]
	v_pk_mul_f32 v[190:191], v[190:191], v[192:193]
	v_pk_mul_f32 v[130:131], v[130:131], v[182:183]
	v_min_f32_e32 v182, 0x60ad78ec, v140
	v_min_f32_e32 v140, 0x60ad78ec, v141
	v_and_b32_e32 v141, 0xffff0000, v188
	v_add_f32_e32 v141, v137, v141
	v_mul_f32_e32 v141, 0xbfb8aa3b, v141
	v_exp_f32_e32 v141, v141
	v_and_b32_e32 v183, 0xffff0000, v186
	v_add_f32_e32 v183, v133, v183
	v_mul_f32_e32 v183, 0xbfb8aa3b, v183
	v_exp_f32_e32 v185, v183
	v_min_f32_e32 v183, 0x60ad78ec, v141
	v_lshlrev_b32_e32 v141, 16, v189
	v_add_f32_e32 v141, v138, v141
	v_add_f32_e32 v140, 1.0, v140
	v_mul_f32_e32 v141, 0xbfb8aa3b, v141
	v_rcp_f32_e32 v184, v140
	v_min_f32_e32 v140, 0x60ad78ec, v185
	v_exp_f32_e32 v141, v141
	v_lshlrev_b32_e32 v185, 16, v187
	v_add_f32_e32 v185, v134, v185
	v_mul_f32_e32 v185, 0xbfb8aa3b, v185
	v_and_b32_e32 v187, 0xffff0000, v187
	v_exp_f32_e32 v188, v185
	v_add_f32_e32 v187, v135, v187
	v_min_f32_e32 v186, 0x60ad78ec, v141
	v_and_b32_e32 v141, 0xffff0000, v189
	v_mul_f32_e32 v187, 0xbfb8aa3b, v187
	v_add_f32_e32 v141, v139, v141
	v_exp_f32_e32 v189, v187
	v_add_f32_e32 v140, 1.0, v140
	v_mul_f32_e32 v141, 0xbfb8aa3b, v141
	v_rcp_f32_e32 v185, v140
	v_min_f32_e32 v140, 0x60ad78ec, v188
	v_exp_f32_e32 v141, v141
	v_add_f32_e32 v140, 1.0, v140
	v_rcp_f32_e32 v188, v140
	v_min_f32_e32 v140, 0x60ad78ec, v189
	v_add_f32_e32 v140, 1.0, v140
	v_min_f32_e32 v187, 0x60ad78ec, v141
	v_rcp_f32_e32 v189, v140
	v_lshlrev_b32_e32 v140, 16, v172
	v_lshlrev_b32_e32 v141, 16, v170
	v_add_f32_e32 v140, v136, v140
	v_add_f32_e32 v141, v132, v141
	v_mul_f32_e32 v140, 0xbfb8aa3b, v140
	v_mul_f32_e32 v141, 0xbfb8aa3b, v141
	v_exp_f32_e32 v140, v140
	v_exp_f32_e32 v141, v141
	v_pk_add_f32 v[182:183], v[182:183], 1.0 op_sel_hi:[1,0]
	v_and_b32_e32 v170, 0xffff0000, v170
	v_pk_mul_f32 v[182:183], v[182:183], v[184:185]
	v_add_f32_e32 v170, v133, v170
	v_pk_mul_f32 v[112:113], v[112:113], v[182:183]
	v_min_f32_e32 v182, 0x60ad78ec, v140
	v_min_f32_e32 v140, 0x60ad78ec, v141
	v_and_b32_e32 v141, 0xffff0000, v172
	v_add_f32_e32 v141, v137, v141
	v_mul_f32_e32 v141, 0xbfb8aa3b, v141
	v_exp_f32_e32 v141, v141
	v_mul_f32_e32 v170, 0xbfb8aa3b, v170
	v_exp_f32_e32 v170, v170
	v_pk_add_f32 v[186:187], v[186:187], 1.0 op_sel_hi:[1,0]
	v_min_f32_e32 v183, 0x60ad78ec, v141
	v_lshlrev_b32_e32 v141, 16, v173
	v_add_f32_e32 v141, v138, v141
	v_pk_mul_f32 v[184:185], v[186:187], v[188:189]
	v_add_f32_e32 v140, 1.0, v140
	v_mul_f32_e32 v141, 0xbfb8aa3b, v141
	v_pk_mul_f32 v[114:115], v[114:115], v[184:185]
	v_rcp_f32_e32 v184, v140
	v_min_f32_e32 v140, 0x60ad78ec, v170
	v_exp_f32_e32 v141, v141
	v_lshlrev_b32_e32 v170, 16, v171
	v_add_f32_e32 v170, v134, v170
	v_mul_f32_e32 v170, 0xbfb8aa3b, v170
	v_and_b32_e32 v171, 0xffff0000, v171
	v_exp_f32_e32 v172, v170
	v_add_f32_e32 v171, v135, v171
	v_min_f32_e32 v170, 0x60ad78ec, v141
	v_and_b32_e32 v141, 0xffff0000, v173
	v_mul_f32_e32 v171, 0xbfb8aa3b, v171
	v_add_f32_e32 v141, v139, v141
	v_exp_f32_e32 v173, v171
	v_add_f32_e32 v140, 1.0, v140
	v_mul_f32_e32 v141, 0xbfb8aa3b, v141
	v_rcp_f32_e32 v185, v140
	v_min_f32_e32 v140, 0x60ad78ec, v172
	v_exp_f32_e32 v141, v141
	v_add_f32_e32 v140, 1.0, v140
	v_rcp_f32_e32 v172, v140
	v_min_f32_e32 v140, 0x60ad78ec, v173
	v_add_f32_e32 v140, 1.0, v140
	v_min_f32_e32 v171, 0x60ad78ec, v141
	v_rcp_f32_e32 v173, v140
	v_lshlrev_b32_e32 v140, 16, v168
	v_lshlrev_b32_e32 v141, 16, v166
	v_add_f32_e32 v140, v136, v140
	v_add_f32_e32 v141, v132, v141
	v_mul_f32_e32 v140, 0xbfb8aa3b, v140
	v_mul_f32_e32 v141, 0xbfb8aa3b, v141
	v_exp_f32_e32 v140, v140
	v_exp_f32_e32 v141, v141
	v_pk_add_f32 v[170:171], v[170:171], 1.0 op_sel_hi:[1,0]
	v_and_b32_e32 v166, 0xffff0000, v166
	v_pk_mul_f32 v[170:171], v[170:171], v[172:173]
	v_add_f32_e32 v166, v133, v166
	v_pk_mul_f32 v[98:99], v[98:99], v[170:171]
	v_min_f32_e32 v170, 0x60ad78ec, v140
	v_min_f32_e32 v140, 0x60ad78ec, v141
	v_and_b32_e32 v141, 0xffff0000, v168
	v_add_f32_e32 v141, v137, v141
	v_mul_f32_e32 v141, 0xbfb8aa3b, v141
	v_exp_f32_e32 v141, v141
	v_mul_f32_e32 v166, 0xbfb8aa3b, v166
	v_exp_f32_e32 v166, v166
	v_add_f32_e32 v140, 1.0, v140
	v_min_f32_e32 v171, 0x60ad78ec, v141
	v_lshlrev_b32_e32 v141, 16, v169
	v_add_f32_e32 v141, v138, v141
	v_mul_f32_e32 v141, 0xbfb8aa3b, v141
	v_rcp_f32_e32 v172, v140
	v_min_f32_e32 v140, 0x60ad78ec, v166
	v_exp_f32_e32 v141, v141
	v_lshlrev_b32_e32 v166, 16, v167
	v_add_f32_e32 v166, v134, v166
	v_mul_f32_e32 v166, 0xbfb8aa3b, v166
	v_and_b32_e32 v167, 0xffff0000, v167
	v_exp_f32_e32 v168, v166
	v_add_f32_e32 v167, v135, v167
	v_min_f32_e32 v166, 0x60ad78ec, v141
	v_and_b32_e32 v141, 0xffff0000, v169
	v_mul_f32_e32 v167, 0xbfb8aa3b, v167
	v_add_f32_e32 v141, v139, v141
	v_exp_f32_e32 v169, v167
	v_add_f32_e32 v140, 1.0, v140
	v_mul_f32_e32 v141, 0xbfb8aa3b, v141
	v_rcp_f32_e32 v173, v140
	v_min_f32_e32 v140, 0x60ad78ec, v168
	v_exp_f32_e32 v141, v141
	v_add_f32_e32 v140, 1.0, v140
	v_rcp_f32_e32 v168, v140
	v_min_f32_e32 v140, 0x60ad78ec, v169
	v_add_f32_e32 v140, 1.0, v140
	v_min_f32_e32 v167, 0x60ad78ec, v141
	v_rcp_f32_e32 v169, v140
	v_lshlrev_b32_e32 v140, 16, v164
	v_lshlrev_b32_e32 v141, 16, v162
	v_add_f32_e32 v140, v136, v140
	v_add_f32_e32 v141, v132, v141
	v_mul_f32_e32 v140, 0xbfb8aa3b, v140
	v_mul_f32_e32 v141, 0xbfb8aa3b, v141
	v_exp_f32_e32 v140, v140
	v_exp_f32_e32 v141, v141
	v_pk_add_f32 v[166:167], v[166:167], 1.0 op_sel_hi:[1,0]
	v_and_b32_e32 v162, 0xffff0000, v162
	v_pk_mul_f32 v[166:167], v[166:167], v[168:169]
	v_add_f32_e32 v162, v133, v162
	v_pk_mul_f32 v[82:83], v[82:83], v[166:167]
	v_min_f32_e32 v166, 0x60ad78ec, v140
	v_min_f32_e32 v140, 0x60ad78ec, v141
	v_and_b32_e32 v141, 0xffff0000, v164
	v_add_f32_e32 v141, v137, v141
	v_mul_f32_e32 v141, 0xbfb8aa3b, v141
	v_exp_f32_e32 v141, v141
	v_mul_f32_e32 v162, 0xbfb8aa3b, v162
	v_exp_f32_e32 v162, v162
	v_add_f32_e32 v140, 1.0, v140
	v_min_f32_e32 v167, 0x60ad78ec, v141
	v_lshlrev_b32_e32 v141, 16, v165
	v_add_f32_e32 v141, v138, v141
	v_mul_f32_e32 v141, 0xbfb8aa3b, v141
	v_rcp_f32_e32 v168, v140
	v_min_f32_e32 v140, 0x60ad78ec, v162
	v_exp_f32_e32 v141, v141
	v_lshlrev_b32_e32 v162, 16, v163
	v_add_f32_e32 v162, v134, v162
	v_mul_f32_e32 v162, 0xbfb8aa3b, v162
	v_and_b32_e32 v163, 0xffff0000, v163
	v_exp_f32_e32 v164, v162
	v_add_f32_e32 v163, v135, v163
	v_min_f32_e32 v162, 0x60ad78ec, v141
	v_and_b32_e32 v141, 0xffff0000, v165
	v_mul_f32_e32 v163, 0xbfb8aa3b, v163
	v_add_f32_e32 v141, v139, v141
	v_exp_f32_e32 v165, v163
	v_add_f32_e32 v140, 1.0, v140
	v_mul_f32_e32 v141, 0xbfb8aa3b, v141
	v_rcp_f32_e32 v169, v140
	v_min_f32_e32 v140, 0x60ad78ec, v164
	v_exp_f32_e32 v141, v141
	v_add_f32_e32 v140, 1.0, v140
	v_rcp_f32_e32 v164, v140
	v_min_f32_e32 v140, 0x60ad78ec, v165
	v_add_f32_e32 v140, 1.0, v140
	v_min_f32_e32 v163, 0x60ad78ec, v141
	v_rcp_f32_e32 v165, v140
	v_lshlrev_b32_e32 v140, 16, v160
	v_lshlrev_b32_e32 v141, 16, v158
	v_add_f32_e32 v140, v136, v140
	v_add_f32_e32 v141, v132, v141
	v_mul_f32_e32 v140, 0xbfb8aa3b, v140
	v_mul_f32_e32 v141, 0xbfb8aa3b, v141
	v_exp_f32_e32 v140, v140
	v_exp_f32_e32 v141, v141
	v_pk_add_f32 v[162:163], v[162:163], 1.0 op_sel_hi:[1,0]
	v_and_b32_e32 v158, 0xffff0000, v158
	v_pk_mul_f32 v[162:163], v[162:163], v[164:165]
	v_add_f32_e32 v158, v133, v158
	v_pk_mul_f32 v[66:67], v[66:67], v[162:163]
	v_min_f32_e32 v162, 0x60ad78ec, v140
	v_min_f32_e32 v140, 0x60ad78ec, v141
	v_and_b32_e32 v141, 0xffff0000, v160
	v_add_f32_e32 v141, v137, v141
	v_mul_f32_e32 v141, 0xbfb8aa3b, v141
	v_exp_f32_e32 v141, v141
	v_mul_f32_e32 v158, 0xbfb8aa3b, v158
	v_exp_f32_e32 v158, v158
	v_add_f32_e32 v140, 1.0, v140
	v_min_f32_e32 v163, 0x60ad78ec, v141
	v_lshlrev_b32_e32 v141, 16, v161
	v_add_f32_e32 v141, v138, v141
	v_mul_f32_e32 v141, 0xbfb8aa3b, v141
	v_rcp_f32_e32 v164, v140
	v_min_f32_e32 v140, 0x60ad78ec, v158
	v_exp_f32_e32 v141, v141
	v_lshlrev_b32_e32 v158, 16, v159
	v_add_f32_e32 v158, v134, v158
	v_mul_f32_e32 v158, 0xbfb8aa3b, v158
	v_and_b32_e32 v159, 0xffff0000, v159
	v_exp_f32_e32 v160, v158
	v_add_f32_e32 v159, v135, v159
	v_min_f32_e32 v158, 0x60ad78ec, v141
	v_and_b32_e32 v141, 0xffff0000, v161
	v_mul_f32_e32 v159, 0xbfb8aa3b, v159
	v_add_f32_e32 v141, v139, v141
	v_exp_f32_e32 v161, v159
	v_add_f32_e32 v140, 1.0, v140
	v_mul_f32_e32 v141, 0xbfb8aa3b, v141
	v_rcp_f32_e32 v165, v140
	v_min_f32_e32 v140, 0x60ad78ec, v160
	v_exp_f32_e32 v141, v141
	v_add_f32_e32 v140, 1.0, v140
	v_rcp_f32_e32 v160, v140
	v_min_f32_e32 v140, 0x60ad78ec, v161
	v_add_f32_e32 v140, 1.0, v140
	v_min_f32_e32 v159, 0x60ad78ec, v141
	v_rcp_f32_e32 v161, v140
	s_waitcnt vmcnt(2)
	v_lshlrev_b32_e32 v140, 16, v156
	v_lshlrev_b32_e32 v141, 16, v154
	v_add_f32_e32 v140, v136, v140
	v_add_f32_e32 v141, v132, v141
	v_mul_f32_e32 v140, 0xbfb8aa3b, v140
	v_mul_f32_e32 v141, 0xbfb8aa3b, v141
	v_exp_f32_e32 v140, v140
	v_exp_f32_e32 v141, v141
	v_pk_add_f32 v[158:159], v[158:159], 1.0 op_sel_hi:[1,0]
	v_and_b32_e32 v154, 0xffff0000, v154
	v_pk_mul_f32 v[158:159], v[158:159], v[160:161]
	v_add_f32_e32 v154, v133, v154
	v_pk_mul_f32 v[50:51], v[50:51], v[158:159]
	v_min_f32_e32 v158, 0x60ad78ec, v140
	v_min_f32_e32 v140, 0x60ad78ec, v141
	v_and_b32_e32 v141, 0xffff0000, v156
	v_add_f32_e32 v141, v137, v141
	v_mul_f32_e32 v141, 0xbfb8aa3b, v141
	v_exp_f32_e32 v141, v141
	v_mul_f32_e32 v154, 0xbfb8aa3b, v154
	v_exp_f32_e32 v154, v154
	v_add_f32_e32 v140, 1.0, v140
	v_min_f32_e32 v159, 0x60ad78ec, v141
	v_lshlrev_b32_e32 v141, 16, v157
	v_add_f32_e32 v141, v138, v141
	v_rcp_f32_e32 v160, v140
	v_min_f32_e32 v140, 0x60ad78ec, v154
	v_mul_f32_e32 v141, 0xbfb8aa3b, v141
	v_lshlrev_b32_e32 v154, 16, v155
	v_exp_f32_e32 v141, v141
	v_add_f32_e32 v154, v134, v154
	v_mul_f32_e32 v154, 0xbfb8aa3b, v154
	v_and_b32_e32 v155, 0xffff0000, v155
	v_exp_f32_e32 v156, v154
	v_add_f32_e32 v155, v135, v155
	v_mul_f32_e32 v155, 0xbfb8aa3b, v155
	v_min_f32_e32 v154, 0x60ad78ec, v141
	v_and_b32_e32 v141, 0xffff0000, v157
	v_exp_f32_e32 v157, v155
	v_add_f32_e32 v140, 1.0, v140
	v_rcp_f32_e32 v161, v140
	v_min_f32_e32 v140, 0x60ad78ec, v156
	v_add_f32_e32 v140, 1.0, v140
	v_rcp_f32_e32 v156, v140
	v_min_f32_e32 v140, 0x60ad78ec, v157
	v_add_f32_e32 v140, 1.0, v140
	v_rcp_f32_e32 v157, v140
	s_waitcnt vmcnt(0)
	v_lshlrev_b32_e32 v140, 16, v152
	v_add_f32_e32 v136, v136, v140
	v_lshlrev_b32_e32 v140, 16, v2
	v_add_f32_e32 v132, v132, v140
	v_mul_f32_e32 v136, 0xbfb8aa3b, v136
	v_mul_f32_e32 v132, 0xbfb8aa3b, v132
	v_exp_f32_e32 v136, v136
	v_exp_f32_e32 v140, v132
	v_and_b32_e32 v2, 0xffff0000, v2
	v_add_f32_e32 v2, v133, v2
	v_min_f32_e32 v132, 0x60ad78ec, v136
	v_min_f32_e32 v136, 0x60ad78ec, v140
	v_and_b32_e32 v140, 0xffff0000, v152
	v_add_f32_e32 v137, v137, v140
	v_mul_f32_e32 v137, 0xbfb8aa3b, v137
	v_exp_f32_e32 v137, v137
	v_add_f32_e32 v133, 1.0, v136
	v_mul_f32_e32 v2, 0xbfb8aa3b, v2
	v_rcp_f32_e32 v136, v133
	v_min_f32_e32 v133, 0x60ad78ec, v137
	v_lshlrev_b32_e32 v137, 16, v153
	v_exp_f32_e32 v2, v2
	v_add_f32_e32 v137, v138, v137
	v_mul_f32_e32 v137, 0xbfb8aa3b, v137
	v_exp_f32_e32 v138, v137
	v_lshlrev_b32_e32 v137, 16, v3
	v_and_b32_e32 v3, 0xffff0000, v3
	v_add_f32_e32 v134, v134, v137
	v_add_f32_e32 v3, v135, v3
	v_min_f32_e32 v2, 0x60ad78ec, v2
	v_mul_f32_e32 v134, 0xbfb8aa3b, v134
	v_mul_f32_e32 v3, 0xbfb8aa3b, v3
	v_exp_f32_e32 v134, v134
	v_add_f32_e32 v2, 1.0, v2
	v_exp_f32_e32 v135, v3
	v_rcp_f32_e32 v137, v2
	v_min_f32_e32 v2, 0x60ad78ec, v138
	v_and_b32_e32 v138, 0xffff0000, v153
	v_add_f32_e32 v138, v139, v138
	v_mul_f32_e32 v138, 0xbfb8aa3b, v138
	v_min_f32_e32 v134, 0x60ad78ec, v134
	v_exp_f32_e32 v138, v138
	v_min_f32_e32 v135, 0x60ad78ec, v135
	v_add_f32_e32 v141, v139, v141
	v_add_f32_e32 v3, 1.0, v134
	v_add_f32_e32 v135, 1.0, v135
	v_mul_f32_e32 v141, 0xbfb8aa3b, v141
	v_rcp_f32_e32 v134, v3
	v_rcp_f32_e32 v135, v135
	v_exp_f32_e32 v141, v141
	v_min_f32_e32 v3, 0x60ad78ec, v138
	v_pk_add_f32 v[2:3], v[2:3], 1.0 op_sel_hi:[1,0]
	v_pk_add_f32 v[132:133], v[132:133], 1.0 op_sel_hi:[1,0]
	v_pk_mul_f32 v[2:3], v[2:3], v[134:135]
	v_min_f32_e32 v155, 0x60ad78ec, v141
	v_pk_mul_f32 v[18:19], v[18:19], v[2:3]
	v_add_u32_e32 v2, s20, v0
	v_pk_add_f32 v[154:155], v[154:155], 1.0 op_sel_hi:[1,0]
	v_ashrrev_i32_e32 v3, 31, v2
	v_pk_mul_f32 v[154:155], v[154:155], v[156:157]
	v_pk_mul_f32 v[152:153], v[132:133], v[136:137]
	v_lshl_add_u64 v[136:137], v[2:3], 2, s[6:7]
	v_lshlrev_b64 v[2:3], 1, v[2:3]
	v_pk_mul_f32 v[34:35], v[34:35], v[154:155]
	v_mad_i64_i32 v[154:155], vcc, v174, s2, v[2:3]
	v_lshl_add_u64 v[154:155], s[30:31], 0, v[154:155]
	v_add_co_u32_e32 v156, vcc, s76, v154
	v_pk_add_f32 v[182:183], v[182:183], 1.0 op_sel_hi:[1,0]
	s_nop 0
	v_addc_co_u32_e32 v157, vcc, 0, v155, vcc
	v_add_co_u32_e32 v154, vcc, s77, v154
	v_pk_mul_f32 v[182:183], v[182:183], v[184:185]
	s_nop 0
	v_addc_co_u32_e32 v155, vcc, 0, v155, vcc
	v_pk_mul_f32 v[96:97], v[96:97], v[182:183]
	v_pk_add_f32 v[158:159], v[158:159], 1.0 op_sel_hi:[1,0]
	global_load_dwordx4 v[132:135], v[136:137], off offset:-4096
	s_nop 0
	global_load_dwordx4 v[136:139], v[136:137], off
	v_pk_mul_f32 v[158:159], v[158:159], v[160:161]
	global_load_dwordx2 v[182:183], v[154:155], off offset:1024
	v_mad_i64_i32 v[154:155], vcc, v175, s2, v[2:3]
	v_lshl_add_u64 v[154:155], s[30:31], 0, v[154:155]
	v_pk_mul_f32 v[32:33], v[32:33], v[158:159]
	v_add_co_u32_e32 v158, vcc, s76, v154
	v_pk_mul_f32 v[16:17], v[16:17], v[152:153]
	s_nop 0
	v_addc_co_u32_e32 v159, vcc, 0, v155, vcc
	v_add_co_u32_e32 v154, vcc, s77, v154
	v_pk_add_f32 v[170:171], v[170:171], 1.0 op_sel_hi:[1,0]
	s_nop 0
	v_addc_co_u32_e32 v155, vcc, 0, v155, vcc
	global_load_dwordx2 v[184:185], v[158:159], off offset:3072
	global_load_dwordx2 v[186:187], v[154:155], off offset:1024
	global_load_dwordx2 v[188:189], v[156:157], off offset:3072
	v_mad_i64_i32 v[152:153], vcc, v176, s2, v[2:3]
	v_lshl_add_u64 v[152:153], s[30:31], 0, v[152:153]
	v_add_co_u32_e32 v154, vcc, s76, v152
	v_pk_add_f32 v[166:167], v[166:167], 1.0 op_sel_hi:[1,0]
	s_nop 0
	v_addc_co_u32_e32 v155, vcc, 0, v153, vcc
	v_add_co_u32_e32 v152, vcc, s77, v152
	v_pk_mul_f32 v[170:171], v[170:171], v[172:173]
	s_nop 0
	v_addc_co_u32_e32 v153, vcc, 0, v153, vcc
	v_mad_i64_i32 v[156:157], vcc, v177, s2, v[2:3]
	v_lshl_add_u64 v[156:157], s[30:31], 0, v[156:157]
	v_add_co_u32_e32 v158, vcc, s76, v156
	v_pk_mul_f32 v[166:167], v[166:167], v[168:169]
	s_nop 0
	v_addc_co_u32_e32 v159, vcc, 0, v157, vcc
	v_add_co_u32_e32 v156, vcc, s77, v156
	v_pk_mul_f32 v[80:81], v[80:81], v[170:171]
	v_pk_mul_f32 v[64:65], v[64:65], v[166:167]
	v_addc_co_u32_e32 v157, vcc, 0, v157, vcc
	global_load_dwordx2 v[170:171], v[154:155], off offset:3072
	global_load_dwordx2 v[172:173], v[152:153], off offset:1024
	global_load_dwordx2 v[166:167], v[158:159], off offset:3072
	global_load_dwordx2 v[168:169], v[156:157], off offset:1024
	v_mad_i64_i32 v[152:153], vcc, v178, s2, v[2:3]
	v_lshl_add_u64 v[152:153], s[30:31], 0, v[152:153]
	v_add_co_u32_e32 v154, vcc, s76, v152
	v_pk_add_f32 v[162:163], v[162:163], 1.0 op_sel_hi:[1,0]
	s_nop 0
	v_addc_co_u32_e32 v155, vcc, 0, v153, vcc
	v_add_co_u32_e32 v152, vcc, s77, v152
	v_pk_mul_f32 v[162:163], v[162:163], v[164:165]
	s_nop 0
	v_addc_co_u32_e32 v153, vcc, 0, v153, vcc
	v_mad_i64_i32 v[156:157], vcc, v179, s2, v[2:3]
	v_lshl_add_u64 v[156:157], s[30:31], 0, v[156:157]
	v_add_co_u32_e32 v158, vcc, s76, v156
	v_pk_mul_f32 v[48:49], v[48:49], v[162:163]
	s_nop 0
	v_addc_co_u32_e32 v159, vcc, 0, v157, vcc
	v_add_co_u32_e32 v156, vcc, s77, v156
	v_pk_mul_f32 v[128:129], v[128:129], v[190:191]
	s_nop 0
	v_addc_co_u32_e32 v157, vcc, 0, v157, vcc
	global_load_dwordx2 v[162:163], v[154:155], off offset:3072
	global_load_dwordx2 v[164:165], v[152:153], off offset:1024
	s_nop 0
	global_load_dwordx2 v[158:159], v[158:159], off offset:3072
	s_nop 0
	global_load_dwordx2 v[160:161], v[156:157], off offset:1024
	v_mad_i64_i32 v[152:153], vcc, v180, s2, v[2:3]
	v_lshl_add_u64 v[152:153], s[30:31], 0, v[152:153]
	v_add_co_u32_e32 v154, vcc, s76, v152
	s_nop 1
	v_addc_co_u32_e32 v155, vcc, 0, v153, vcc
	v_add_co_u32_e32 v152, vcc, s77, v152
	s_nop 1
	v_addc_co_u32_e32 v153, vcc, 0, v153, vcc
	v_mad_i64_i32 v[2:3], vcc, v181, s2, v[2:3]
	v_lshl_add_u64 v[2:3], s[30:31], 0, v[2:3]
	v_add_co_u32_e32 v190, vcc, s76, v2
	s_nop 1
	v_addc_co_u32_e32 v191, vcc, 0, v3, vcc
	v_add_co_u32_e32 v192, vcc, s77, v2
	s_waitcnt vmcnt(11)
	v_lshlrev_b32_e32 v2, 16, v182
	v_add_f32_e32 v2, v136, v2
	v_mul_f32_e32 v2, 0xbfb8aa3b, v2
	v_exp_f32_e32 v140, v2
	s_waitcnt vmcnt(8)
	v_lshlrev_b32_e32 v2, 16, v188
	v_add_f32_e32 v2, v132, v2
	v_mul_f32_e32 v2, 0xbfb8aa3b, v2
	v_exp_f32_e32 v141, v2
	v_addc_co_u32_e32 v193, vcc, 0, v3, vcc
	global_load_dwordx2 v[154:155], v[154:155], off offset:3072
	s_nop 0
	global_load_dwordx2 v[156:157], v[152:153], off offset:1024
	global_load_dwordx2 v[2:3], v[190:191], off offset:3072
	s_nop 0
	global_load_dwordx2 v[152:153], v[192:193], off offset:1024
	v_min_f32_e32 v190, 0x60ad78ec, v140
	v_min_f32_e32 v140, 0x60ad78ec, v141
	v_and_b32_e32 v141, 0xffff0000, v182
	v_add_f32_e32 v141, v137, v141
	v_mul_f32_e32 v141, 0xbfb8aa3b, v141
	v_exp_f32_e32 v141, v141
	v_and_b32_e32 v182, 0xffff0000, v188
	v_add_f32_e32 v182, v133, v182
	v_mul_f32_e32 v182, 0xbfb8aa3b, v182
	v_exp_f32_e32 v182, v182
	v_min_f32_e32 v191, 0x60ad78ec, v141
	v_lshlrev_b32_e32 v141, 16, v183
	v_add_f32_e32 v141, v138, v141
	v_mul_f32_e32 v141, 0xbfb8aa3b, v141
	v_add_f32_e32 v140, 1.0, v140
	v_exp_f32_e32 v141, v141
	v_rcp_f32_e32 v192, v140
	v_min_f32_e32 v140, 0x60ad78ec, v182
	v_lshlrev_b32_e32 v182, 16, v189
	v_add_f32_e32 v182, v134, v182
	v_mul_f32_e32 v182, 0xbfb8aa3b, v182
	v_exp_f32_e32 v188, v182
	v_min_f32_e32 v182, 0x60ad78ec, v141
	v_and_b32_e32 v141, 0xffff0000, v183
	v_and_b32_e32 v183, 0xffff0000, v189
	v_add_f32_e32 v183, v135, v183
	v_mul_f32_e32 v183, 0xbfb8aa3b, v183
	v_add_f32_e32 v141, v139, v141
	v_exp_f32_e32 v189, v183
	v_add_f32_e32 v140, 1.0, v140
	v_mul_f32_e32 v141, 0xbfb8aa3b, v141
	v_rcp_f32_e32 v193, v140
	v_min_f32_e32 v140, 0x60ad78ec, v188
	v_exp_f32_e32 v141, v141
	v_add_f32_e32 v140, 1.0, v140
	v_rcp_f32_e32 v188, v140
	v_min_f32_e32 v140, 0x60ad78ec, v189
	v_add_f32_e32 v140, 1.0, v140
	v_min_f32_e32 v183, 0x60ad78ec, v141
	v_rcp_f32_e32 v189, v140
	v_lshlrev_b32_e32 v140, 16, v186
	v_lshlrev_b32_e32 v141, 16, v184
	v_add_f32_e32 v140, v136, v140
	v_add_f32_e32 v141, v132, v141
	v_mul_f32_e32 v140, 0xbfb8aa3b, v140
	v_mul_f32_e32 v141, 0xbfb8aa3b, v141
	v_exp_f32_e32 v140, v140
	v_exp_f32_e32 v141, v141
	v_pk_add_f32 v[182:183], v[182:183], 1.0 op_sel_hi:[1,0]
	v_pk_add_f32 v[190:191], v[190:191], 1.0 op_sel_hi:[1,0]
	v_pk_mul_f32 v[182:183], v[182:183], v[188:189]
	v_pk_mul_f32 v[190:191], v[190:191], v[192:193]
	v_pk_mul_f32 v[126:127], v[126:127], v[182:183]
	v_min_f32_e32 v182, 0x60ad78ec, v140
	v_min_f32_e32 v140, 0x60ad78ec, v141
	v_and_b32_e32 v141, 0xffff0000, v186
	v_add_f32_e32 v141, v137, v141
	v_mul_f32_e32 v141, 0xbfb8aa3b, v141
	v_exp_f32_e32 v141, v141
	v_and_b32_e32 v183, 0xffff0000, v184
	v_add_f32_e32 v183, v133, v183
	v_mul_f32_e32 v183, 0xbfb8aa3b, v183
	v_exp_f32_e32 v184, v183
	v_min_f32_e32 v183, 0x60ad78ec, v141
	v_lshlrev_b32_e32 v141, 16, v187
	v_add_f32_e32 v141, v138, v141
	v_add_f32_e32 v140, 1.0, v140
	v_mul_f32_e32 v141, 0xbfb8aa3b, v141
	v_rcp_f32_e32 v188, v140
	v_min_f32_e32 v140, 0x60ad78ec, v184
	v_exp_f32_e32 v141, v141
	v_lshlrev_b32_e32 v184, 16, v185
	v_add_f32_e32 v184, v134, v184
	v_mul_f32_e32 v184, 0xbfb8aa3b, v184
	v_and_b32_e32 v185, 0xffff0000, v185
	v_exp_f32_e32 v186, v184
	v_add_f32_e32 v185, v135, v185
	v_min_f32_e32 v184, 0x60ad78ec, v141
	v_and_b32_e32 v141, 0xffff0000, v187
	v_mul_f32_e32 v185, 0xbfb8aa3b, v185
	v_add_f32_e32 v141, v139, v141
	v_exp_f32_e32 v187, v185
	v_add_f32_e32 v140, 1.0, v140
	v_mul_f32_e32 v141, 0xbfb8aa3b, v141
	v_rcp_f32_e32 v189, v140
	v_min_f32_e32 v140, 0x60ad78ec, v186
	v_exp_f32_e32 v141, v141
	v_add_f32_e32 v140, 1.0, v140
	v_rcp_f32_e32 v186, v140
	v_min_f32_e32 v140, 0x60ad78ec, v187
	v_add_f32_e32 v140, 1.0, v140
	v_min_f32_e32 v185, 0x60ad78ec, v141
	v_rcp_f32_e32 v187, v140
	s_waitcnt vmcnt(10)
	v_lshlrev_b32_e32 v140, 16, v172
	v_lshlrev_b32_e32 v141, 16, v170
	v_add_f32_e32 v140, v136, v140
	v_add_f32_e32 v141, v132, v141
	v_mul_f32_e32 v140, 0xbfb8aa3b, v140
	v_mul_f32_e32 v141, 0xbfb8aa3b, v141
	v_exp_f32_e32 v140, v140
	v_exp_f32_e32 v141, v141
	v_pk_add_f32 v[182:183], v[182:183], 1.0 op_sel_hi:[1,0]
	v_and_b32_e32 v170, 0xffff0000, v170
	v_pk_mul_f32 v[182:183], v[182:183], v[188:189]
	v_add_f32_e32 v170, v133, v170
	v_pk_mul_f32 v[108:109], v[108:109], v[182:183]
	v_min_f32_e32 v182, 0x60ad78ec, v140
	v_min_f32_e32 v140, 0x60ad78ec, v141
	v_and_b32_e32 v141, 0xffff0000, v172
	v_add_f32_e32 v141, v137, v141
	v_mul_f32_e32 v141, 0xbfb8aa3b, v141
	v_exp_f32_e32 v141, v141
	v_mul_f32_e32 v170, 0xbfb8aa3b, v170
	v_exp_f32_e32 v170, v170
	v_pk_add_f32 v[184:185], v[184:185], 1.0 op_sel_hi:[1,0]
	v_min_f32_e32 v183, 0x60ad78ec, v141
	v_lshlrev_b32_e32 v141, 16, v173
	v_add_f32_e32 v141, v138, v141
	v_pk_mul_f32 v[184:185], v[184:185], v[186:187]
	v_add_f32_e32 v140, 1.0, v140
	v_mul_f32_e32 v141, 0xbfb8aa3b, v141
	v_pk_mul_f32 v[110:111], v[110:111], v[184:185]
	v_rcp_f32_e32 v184, v140
	v_min_f32_e32 v140, 0x60ad78ec, v170
	v_exp_f32_e32 v141, v141
	v_lshlrev_b32_e32 v170, 16, v171
	v_add_f32_e32 v170, v134, v170
	v_mul_f32_e32 v170, 0xbfb8aa3b, v170
	v_and_b32_e32 v171, 0xffff0000, v171
	v_exp_f32_e32 v172, v170
	v_add_f32_e32 v171, v135, v171
	v_min_f32_e32 v170, 0x60ad78ec, v141
	v_and_b32_e32 v141, 0xffff0000, v173
	v_mul_f32_e32 v171, 0xbfb8aa3b, v171
	v_add_f32_e32 v141, v139, v141
	v_exp_f32_e32 v173, v171
	v_add_f32_e32 v140, 1.0, v140
	v_mul_f32_e32 v141, 0xbfb8aa3b, v141
	v_rcp_f32_e32 v185, v140
	v_min_f32_e32 v140, 0x60ad78ec, v172
	v_exp_f32_e32 v141, v141
	v_add_f32_e32 v140, 1.0, v140
	v_rcp_f32_e32 v172, v140
	v_min_f32_e32 v140, 0x60ad78ec, v173
	v_add_f32_e32 v140, 1.0, v140
	v_min_f32_e32 v171, 0x60ad78ec, v141
	v_rcp_f32_e32 v173, v140
	s_waitcnt vmcnt(8)
	v_lshlrev_b32_e32 v140, 16, v168
	v_lshlrev_b32_e32 v141, 16, v166
	v_add_f32_e32 v140, v136, v140
	v_add_f32_e32 v141, v132, v141
	v_mul_f32_e32 v140, 0xbfb8aa3b, v140
	v_mul_f32_e32 v141, 0xbfb8aa3b, v141
	v_exp_f32_e32 v140, v140
	v_exp_f32_e32 v141, v141
	v_pk_add_f32 v[170:171], v[170:171], 1.0 op_sel_hi:[1,0]
	v_and_b32_e32 v166, 0xffff0000, v166
	v_pk_mul_f32 v[170:171], v[170:171], v[172:173]
	v_add_f32_e32 v166, v133, v166
	v_pk_mul_f32 v[94:95], v[94:95], v[170:171]
	v_min_f32_e32 v170, 0x60ad78ec, v140
	v_min_f32_e32 v140, 0x60ad78ec, v141
	v_and_b32_e32 v141, 0xffff0000, v168
	v_add_f32_e32 v141, v137, v141
	v_mul_f32_e32 v141, 0xbfb8aa3b, v141
	v_exp_f32_e32 v141, v141
	v_mul_f32_e32 v166, 0xbfb8aa3b, v166
	v_exp_f32_e32 v166, v166
	v_add_f32_e32 v140, 1.0, v140
	v_min_f32_e32 v171, 0x60ad78ec, v141
	v_lshlrev_b32_e32 v141, 16, v169
	v_add_f32_e32 v141, v138, v141
	v_mul_f32_e32 v141, 0xbfb8aa3b, v141
	v_rcp_f32_e32 v172, v140
	v_min_f32_e32 v140, 0x60ad78ec, v166
	v_exp_f32_e32 v141, v141
	v_lshlrev_b32_e32 v166, 16, v167
	v_add_f32_e32 v166, v134, v166
	v_mul_f32_e32 v166, 0xbfb8aa3b, v166
	v_and_b32_e32 v167, 0xffff0000, v167
	v_exp_f32_e32 v168, v166
	v_add_f32_e32 v167, v135, v167
	v_min_f32_e32 v166, 0x60ad78ec, v141
	v_and_b32_e32 v141, 0xffff0000, v169
	v_mul_f32_e32 v167, 0xbfb8aa3b, v167
	v_add_f32_e32 v141, v139, v141
	v_exp_f32_e32 v169, v167
	v_add_f32_e32 v140, 1.0, v140
	v_mul_f32_e32 v141, 0xbfb8aa3b, v141
	v_rcp_f32_e32 v173, v140
	v_min_f32_e32 v140, 0x60ad78ec, v168
	v_exp_f32_e32 v141, v141
	v_add_f32_e32 v140, 1.0, v140
	v_rcp_f32_e32 v168, v140
	v_min_f32_e32 v140, 0x60ad78ec, v169
	v_add_f32_e32 v140, 1.0, v140
	v_min_f32_e32 v167, 0x60ad78ec, v141
	v_rcp_f32_e32 v169, v140
	s_waitcnt vmcnt(6)
	v_lshlrev_b32_e32 v140, 16, v164
	v_lshlrev_b32_e32 v141, 16, v162
	v_add_f32_e32 v140, v136, v140
	v_add_f32_e32 v141, v132, v141
	v_mul_f32_e32 v140, 0xbfb8aa3b, v140
	v_mul_f32_e32 v141, 0xbfb8aa3b, v141
	v_exp_f32_e32 v140, v140
	v_exp_f32_e32 v141, v141
	v_pk_add_f32 v[166:167], v[166:167], 1.0 op_sel_hi:[1,0]
	v_and_b32_e32 v162, 0xffff0000, v162
	v_pk_mul_f32 v[166:167], v[166:167], v[168:169]
	v_add_f32_e32 v162, v133, v162
	v_pk_mul_f32 v[78:79], v[78:79], v[166:167]
	v_min_f32_e32 v166, 0x60ad78ec, v140
	v_min_f32_e32 v140, 0x60ad78ec, v141
	v_and_b32_e32 v141, 0xffff0000, v164
	v_add_f32_e32 v141, v137, v141
	v_mul_f32_e32 v141, 0xbfb8aa3b, v141
	v_exp_f32_e32 v141, v141
	v_mul_f32_e32 v162, 0xbfb8aa3b, v162
	v_exp_f32_e32 v162, v162
	v_add_f32_e32 v140, 1.0, v140
	v_min_f32_e32 v167, 0x60ad78ec, v141
	v_lshlrev_b32_e32 v141, 16, v165
	v_add_f32_e32 v141, v138, v141
	v_mul_f32_e32 v141, 0xbfb8aa3b, v141
	v_rcp_f32_e32 v168, v140
	v_min_f32_e32 v140, 0x60ad78ec, v162
	v_exp_f32_e32 v141, v141
	v_lshlrev_b32_e32 v162, 16, v163
	v_add_f32_e32 v162, v134, v162
	v_mul_f32_e32 v162, 0xbfb8aa3b, v162
	v_and_b32_e32 v163, 0xffff0000, v163
	v_exp_f32_e32 v164, v162
	v_add_f32_e32 v163, v135, v163
	v_min_f32_e32 v162, 0x60ad78ec, v141
	v_and_b32_e32 v141, 0xffff0000, v165
	v_mul_f32_e32 v163, 0xbfb8aa3b, v163
	v_add_f32_e32 v141, v139, v141
	v_exp_f32_e32 v165, v163
	v_add_f32_e32 v140, 1.0, v140
	v_mul_f32_e32 v141, 0xbfb8aa3b, v141
	v_rcp_f32_e32 v169, v140
	v_min_f32_e32 v140, 0x60ad78ec, v164
	v_exp_f32_e32 v141, v141
	v_add_f32_e32 v140, 1.0, v140
	v_rcp_f32_e32 v164, v140
	v_min_f32_e32 v140, 0x60ad78ec, v165
	v_add_f32_e32 v140, 1.0, v140
	v_min_f32_e32 v163, 0x60ad78ec, v141
	v_rcp_f32_e32 v165, v140
	s_waitcnt vmcnt(4)
	v_lshlrev_b32_e32 v140, 16, v160
	v_lshlrev_b32_e32 v141, 16, v158
	v_add_f32_e32 v140, v136, v140
	v_add_f32_e32 v141, v132, v141
	v_mul_f32_e32 v140, 0xbfb8aa3b, v140
	v_mul_f32_e32 v141, 0xbfb8aa3b, v141
	v_exp_f32_e32 v140, v140
	v_exp_f32_e32 v141, v141
	v_pk_add_f32 v[162:163], v[162:163], 1.0 op_sel_hi:[1,0]
	v_and_b32_e32 v158, 0xffff0000, v158
	v_pk_mul_f32 v[162:163], v[162:163], v[164:165]
	v_add_f32_e32 v158, v133, v158
	v_pk_mul_f32 v[62:63], v[62:63], v[162:163]
	v_min_f32_e32 v162, 0x60ad78ec, v140
	v_min_f32_e32 v140, 0x60ad78ec, v141
	v_and_b32_e32 v141, 0xffff0000, v160
	v_add_f32_e32 v141, v137, v141
	v_mul_f32_e32 v141, 0xbfb8aa3b, v141
	v_exp_f32_e32 v141, v141
	v_mul_f32_e32 v158, 0xbfb8aa3b, v158
	v_exp_f32_e32 v158, v158
	v_add_f32_e32 v140, 1.0, v140
	v_min_f32_e32 v163, 0x60ad78ec, v141
	v_lshlrev_b32_e32 v141, 16, v161
	v_add_f32_e32 v141, v138, v141
	v_mul_f32_e32 v141, 0xbfb8aa3b, v141
	v_rcp_f32_e32 v164, v140
	v_min_f32_e32 v140, 0x60ad78ec, v158
	v_exp_f32_e32 v141, v141
	v_lshlrev_b32_e32 v158, 16, v159
	v_add_f32_e32 v158, v134, v158
	v_mul_f32_e32 v158, 0xbfb8aa3b, v158
	v_and_b32_e32 v159, 0xffff0000, v159
	v_exp_f32_e32 v160, v158
	v_add_f32_e32 v159, v135, v159
	v_min_f32_e32 v158, 0x60ad78ec, v141
	v_and_b32_e32 v141, 0xffff0000, v161
	v_mul_f32_e32 v159, 0xbfb8aa3b, v159
	v_add_f32_e32 v141, v139, v141
	v_exp_f32_e32 v161, v159
	v_add_f32_e32 v140, 1.0, v140
	v_mul_f32_e32 v141, 0xbfb8aa3b, v141
	v_rcp_f32_e32 v165, v140
	v_min_f32_e32 v140, 0x60ad78ec, v160
	v_exp_f32_e32 v141, v141
	v_add_f32_e32 v140, 1.0, v140
	v_rcp_f32_e32 v160, v140
	v_min_f32_e32 v140, 0x60ad78ec, v161
	v_add_f32_e32 v140, 1.0, v140
	v_min_f32_e32 v159, 0x60ad78ec, v141
	v_rcp_f32_e32 v161, v140
	s_waitcnt vmcnt(2)
	v_lshlrev_b32_e32 v140, 16, v156
	v_lshlrev_b32_e32 v141, 16, v154
	v_add_f32_e32 v140, v136, v140
	v_add_f32_e32 v141, v132, v141
	v_mul_f32_e32 v140, 0xbfb8aa3b, v140
	v_mul_f32_e32 v141, 0xbfb8aa3b, v141
	v_exp_f32_e32 v140, v140
	v_exp_f32_e32 v141, v141
	v_pk_add_f32 v[158:159], v[158:159], 1.0 op_sel_hi:[1,0]
	v_and_b32_e32 v154, 0xffff0000, v154
	v_pk_mul_f32 v[158:159], v[158:159], v[160:161]
	v_add_f32_e32 v154, v133, v154
	v_pk_mul_f32 v[46:47], v[46:47], v[158:159]
	v_min_f32_e32 v158, 0x60ad78ec, v140
	v_min_f32_e32 v140, 0x60ad78ec, v141
	v_and_b32_e32 v141, 0xffff0000, v156
	v_add_f32_e32 v141, v137, v141
	v_mul_f32_e32 v141, 0xbfb8aa3b, v141
	v_exp_f32_e32 v141, v141
	v_mul_f32_e32 v154, 0xbfb8aa3b, v154
	v_exp_f32_e32 v154, v154
	v_add_f32_e32 v140, 1.0, v140
	v_min_f32_e32 v159, 0x60ad78ec, v141
	v_lshlrev_b32_e32 v141, 16, v157
	v_add_f32_e32 v141, v138, v141
	v_rcp_f32_e32 v160, v140
	v_min_f32_e32 v140, 0x60ad78ec, v154
	v_mul_f32_e32 v141, 0xbfb8aa3b, v141
	v_lshlrev_b32_e32 v154, 16, v155
	v_exp_f32_e32 v141, v141
	v_add_f32_e32 v154, v134, v154
	v_mul_f32_e32 v154, 0xbfb8aa3b, v154
	v_and_b32_e32 v155, 0xffff0000, v155
	v_exp_f32_e32 v156, v154
	v_add_f32_e32 v155, v135, v155
	v_mul_f32_e32 v155, 0xbfb8aa3b, v155
	v_min_f32_e32 v154, 0x60ad78ec, v141
	v_and_b32_e32 v141, 0xffff0000, v157
	v_exp_f32_e32 v157, v155
	v_add_f32_e32 v140, 1.0, v140
	v_rcp_f32_e32 v161, v140
	v_min_f32_e32 v140, 0x60ad78ec, v156
	v_add_f32_e32 v140, 1.0, v140
	v_rcp_f32_e32 v156, v140
	v_min_f32_e32 v140, 0x60ad78ec, v157
	v_add_f32_e32 v140, 1.0, v140
	v_rcp_f32_e32 v157, v140
	s_waitcnt vmcnt(0)
	v_lshlrev_b32_e32 v140, 16, v152
	v_add_f32_e32 v136, v136, v140
	v_lshlrev_b32_e32 v140, 16, v2
	v_add_f32_e32 v132, v132, v140
	v_mul_f32_e32 v136, 0xbfb8aa3b, v136
	v_mul_f32_e32 v132, 0xbfb8aa3b, v132
	v_exp_f32_e32 v136, v136
	v_exp_f32_e32 v140, v132
	v_and_b32_e32 v2, 0xffff0000, v2
	v_add_f32_e32 v2, v133, v2
	v_min_f32_e32 v132, 0x60ad78ec, v136
	v_min_f32_e32 v136, 0x60ad78ec, v140
	v_and_b32_e32 v140, 0xffff0000, v152
	v_add_f32_e32 v137, v137, v140
	v_mul_f32_e32 v137, 0xbfb8aa3b, v137
	v_exp_f32_e32 v137, v137
	v_add_f32_e32 v133, 1.0, v136
	v_mul_f32_e32 v2, 0xbfb8aa3b, v2
	v_rcp_f32_e32 v136, v133
	v_min_f32_e32 v133, 0x60ad78ec, v137
	v_lshlrev_b32_e32 v137, 16, v153
	v_exp_f32_e32 v2, v2
	v_add_f32_e32 v137, v138, v137
	v_mul_f32_e32 v137, 0xbfb8aa3b, v137
	v_exp_f32_e32 v138, v137
	v_lshlrev_b32_e32 v137, 16, v3
	v_and_b32_e32 v3, 0xffff0000, v3
	v_add_f32_e32 v134, v134, v137
	v_add_f32_e32 v3, v135, v3
	v_min_f32_e32 v2, 0x60ad78ec, v2
	v_mul_f32_e32 v134, 0xbfb8aa3b, v134
	v_mul_f32_e32 v3, 0xbfb8aa3b, v3
	v_exp_f32_e32 v134, v134
	v_add_f32_e32 v2, 1.0, v2
	v_exp_f32_e32 v135, v3
	v_rcp_f32_e32 v137, v2
	v_min_f32_e32 v2, 0x60ad78ec, v138
	v_and_b32_e32 v138, 0xffff0000, v153
	v_add_f32_e32 v138, v139, v138
	v_mul_f32_e32 v138, 0xbfb8aa3b, v138
	v_min_f32_e32 v134, 0x60ad78ec, v134
	v_exp_f32_e32 v138, v138
	v_min_f32_e32 v135, 0x60ad78ec, v135
	v_add_f32_e32 v141, v139, v141
	v_add_f32_e32 v3, 1.0, v134
	v_add_f32_e32 v135, 1.0, v135
	v_mul_f32_e32 v141, 0xbfb8aa3b, v141
	v_rcp_f32_e32 v134, v3
	v_rcp_f32_e32 v135, v135
	v_exp_f32_e32 v141, v141
	v_min_f32_e32 v3, 0x60ad78ec, v138
	v_pk_add_f32 v[2:3], v[2:3], 1.0 op_sel_hi:[1,0]
	v_pk_add_f32 v[132:133], v[132:133], 1.0 op_sel_hi:[1,0]
	v_pk_mul_f32 v[2:3], v[2:3], v[134:135]
	v_min_f32_e32 v155, 0x60ad78ec, v141
	v_pk_mul_f32 v[14:15], v[14:15], v[2:3]
	v_add_u32_e32 v2, s82, v0
	v_pk_add_f32 v[154:155], v[154:155], 1.0 op_sel_hi:[1,0]
	v_ashrrev_i32_e32 v3, 31, v2
	v_pk_mul_f32 v[154:155], v[154:155], v[156:157]
	v_pk_mul_f32 v[152:153], v[132:133], v[136:137]
	v_lshl_add_u64 v[136:137], v[2:3], 2, s[6:7]
	v_lshlrev_b64 v[2:3], 1, v[2:3]
	v_pk_mul_f32 v[30:31], v[30:31], v[154:155]
	v_mad_i64_i32 v[154:155], vcc, v174, s2, v[2:3]
	v_lshl_add_u64 v[154:155], s[30:31], 0, v[154:155]
	v_add_co_u32_e32 v156, vcc, s76, v154
	v_pk_add_f32 v[182:183], v[182:183], 1.0 op_sel_hi:[1,0]
	s_nop 0
	v_addc_co_u32_e32 v157, vcc, 0, v155, vcc
	v_add_co_u32_e32 v154, vcc, s77, v154
	v_pk_mul_f32 v[182:183], v[182:183], v[184:185]
	s_nop 0
	v_addc_co_u32_e32 v155, vcc, 0, v155, vcc
	v_pk_mul_f32 v[92:93], v[92:93], v[182:183]
	v_pk_add_f32 v[158:159], v[158:159], 1.0 op_sel_hi:[1,0]
	global_load_dwordx4 v[132:135], v[136:137], off offset:-4096
	s_nop 0
	global_load_dwordx4 v[136:139], v[136:137], off
	v_pk_mul_f32 v[158:159], v[158:159], v[160:161]
	global_load_dwordx2 v[182:183], v[154:155], off offset:1024
	v_mad_i64_i32 v[154:155], vcc, v175, s2, v[2:3]
	v_lshl_add_u64 v[154:155], s[30:31], 0, v[154:155]
	v_pk_mul_f32 v[28:29], v[28:29], v[158:159]
	v_add_co_u32_e32 v158, vcc, s76, v154
	v_pk_mul_f32 v[12:13], v[12:13], v[152:153]
	s_nop 0
	v_addc_co_u32_e32 v159, vcc, 0, v155, vcc
	v_add_co_u32_e32 v154, vcc, s77, v154
	v_pk_add_f32 v[170:171], v[170:171], 1.0 op_sel_hi:[1,0]
	s_nop 0
	v_addc_co_u32_e32 v155, vcc, 0, v155, vcc
	global_load_dwordx2 v[184:185], v[158:159], off offset:3072
	global_load_dwordx2 v[186:187], v[154:155], off offset:1024
	global_load_dwordx2 v[188:189], v[156:157], off offset:3072
	v_mad_i64_i32 v[152:153], vcc, v176, s2, v[2:3]
	v_lshl_add_u64 v[152:153], s[30:31], 0, v[152:153]
	v_add_co_u32_e32 v154, vcc, s76, v152
	v_pk_add_f32 v[166:167], v[166:167], 1.0 op_sel_hi:[1,0]
	s_nop 0
	v_addc_co_u32_e32 v155, vcc, 0, v153, vcc
	v_add_co_u32_e32 v152, vcc, s77, v152
	v_pk_mul_f32 v[170:171], v[170:171], v[172:173]
	s_nop 0
	v_addc_co_u32_e32 v153, vcc, 0, v153, vcc
	v_mad_i64_i32 v[156:157], vcc, v177, s2, v[2:3]
	v_lshl_add_u64 v[156:157], s[30:31], 0, v[156:157]
	v_add_co_u32_e32 v158, vcc, s76, v156
	v_pk_mul_f32 v[166:167], v[166:167], v[168:169]
	s_nop 0
	v_addc_co_u32_e32 v159, vcc, 0, v157, vcc
	v_add_co_u32_e32 v156, vcc, s77, v156
	v_pk_mul_f32 v[76:77], v[76:77], v[170:171]
	v_pk_mul_f32 v[60:61], v[60:61], v[166:167]
	v_addc_co_u32_e32 v157, vcc, 0, v157, vcc
	global_load_dwordx2 v[170:171], v[154:155], off offset:3072
	global_load_dwordx2 v[172:173], v[152:153], off offset:1024
	global_load_dwordx2 v[166:167], v[158:159], off offset:3072
	global_load_dwordx2 v[168:169], v[156:157], off offset:1024
	v_mad_i64_i32 v[152:153], vcc, v178, s2, v[2:3]
	v_lshl_add_u64 v[152:153], s[30:31], 0, v[152:153]
	v_add_co_u32_e32 v154, vcc, s76, v152
	v_pk_add_f32 v[162:163], v[162:163], 1.0 op_sel_hi:[1,0]
	s_nop 0
	v_addc_co_u32_e32 v155, vcc, 0, v153, vcc
	v_add_co_u32_e32 v152, vcc, s77, v152
	v_pk_mul_f32 v[162:163], v[162:163], v[164:165]
	s_nop 0
	v_addc_co_u32_e32 v153, vcc, 0, v153, vcc
	v_mad_i64_i32 v[156:157], vcc, v179, s2, v[2:3]
	v_lshl_add_u64 v[156:157], s[30:31], 0, v[156:157]
	v_add_co_u32_e32 v158, vcc, s76, v156
	v_pk_mul_f32 v[44:45], v[44:45], v[162:163]
	s_nop 0
	v_addc_co_u32_e32 v159, vcc, 0, v157, vcc
	v_add_co_u32_e32 v156, vcc, s77, v156
	v_pk_mul_f32 v[124:125], v[124:125], v[190:191]
	s_nop 0
	v_addc_co_u32_e32 v157, vcc, 0, v157, vcc
	global_load_dwordx2 v[162:163], v[154:155], off offset:3072
	global_load_dwordx2 v[164:165], v[152:153], off offset:1024
	s_nop 0
	global_load_dwordx2 v[158:159], v[158:159], off offset:3072
	s_nop 0
	global_load_dwordx2 v[160:161], v[156:157], off offset:1024
	v_mad_i64_i32 v[152:153], vcc, v180, s2, v[2:3]
	v_lshl_add_u64 v[152:153], s[30:31], 0, v[152:153]
	v_add_co_u32_e32 v154, vcc, s76, v152
	s_nop 1
	v_addc_co_u32_e32 v155, vcc, 0, v153, vcc
	v_add_co_u32_e32 v152, vcc, s77, v152
	s_nop 1
	v_addc_co_u32_e32 v153, vcc, 0, v153, vcc
	v_mad_i64_i32 v[2:3], vcc, v181, s2, v[2:3]
	v_lshl_add_u64 v[2:3], s[30:31], 0, v[2:3]
	v_add_co_u32_e32 v190, vcc, s76, v2
	s_nop 1
	v_addc_co_u32_e32 v191, vcc, 0, v3, vcc
	v_add_co_u32_e32 v192, vcc, s77, v2
	s_waitcnt vmcnt(11)
	v_lshlrev_b32_e32 v2, 16, v182
	v_add_f32_e32 v2, v136, v2
	v_mul_f32_e32 v2, 0xbfb8aa3b, v2
	v_exp_f32_e32 v140, v2
	s_waitcnt vmcnt(8)
	v_lshlrev_b32_e32 v2, 16, v188
	v_add_f32_e32 v2, v132, v2
	v_mul_f32_e32 v2, 0xbfb8aa3b, v2
	v_exp_f32_e32 v141, v2
	v_addc_co_u32_e32 v193, vcc, 0, v3, vcc
	global_load_dwordx2 v[154:155], v[154:155], off offset:3072
	s_nop 0
	global_load_dwordx2 v[156:157], v[152:153], off offset:1024
	global_load_dwordx2 v[2:3], v[190:191], off offset:3072
	s_nop 0
	global_load_dwordx2 v[152:153], v[192:193], off offset:1024
	v_min_f32_e32 v190, 0x60ad78ec, v140
	v_min_f32_e32 v140, 0x60ad78ec, v141
	v_and_b32_e32 v141, 0xffff0000, v182
	v_add_f32_e32 v141, v137, v141
	v_mul_f32_e32 v141, 0xbfb8aa3b, v141
	v_exp_f32_e32 v141, v141
	v_and_b32_e32 v182, 0xffff0000, v188
	v_add_f32_e32 v182, v133, v182
	v_mul_f32_e32 v182, 0xbfb8aa3b, v182
	v_exp_f32_e32 v182, v182
	v_min_f32_e32 v191, 0x60ad78ec, v141
	v_lshlrev_b32_e32 v141, 16, v183
	v_add_f32_e32 v141, v138, v141
	v_mul_f32_e32 v141, 0xbfb8aa3b, v141
	v_add_f32_e32 v140, 1.0, v140
	v_exp_f32_e32 v141, v141
	v_rcp_f32_e32 v192, v140
	v_min_f32_e32 v140, 0x60ad78ec, v182
	v_lshlrev_b32_e32 v182, 16, v189
	v_add_f32_e32 v182, v134, v182
	v_mul_f32_e32 v182, 0xbfb8aa3b, v182
	v_exp_f32_e32 v188, v182
	v_min_f32_e32 v182, 0x60ad78ec, v141
	v_and_b32_e32 v141, 0xffff0000, v183
	v_and_b32_e32 v183, 0xffff0000, v189
	v_add_f32_e32 v183, v135, v183
	v_mul_f32_e32 v183, 0xbfb8aa3b, v183
	v_add_f32_e32 v141, v139, v141
	v_exp_f32_e32 v189, v183
	v_add_f32_e32 v140, 1.0, v140
	v_mul_f32_e32 v141, 0xbfb8aa3b, v141
	v_rcp_f32_e32 v193, v140
	v_min_f32_e32 v140, 0x60ad78ec, v188
	v_exp_f32_e32 v141, v141
	v_add_f32_e32 v140, 1.0, v140
	v_rcp_f32_e32 v188, v140
	v_min_f32_e32 v140, 0x60ad78ec, v189
	v_add_f32_e32 v140, 1.0, v140
	v_min_f32_e32 v183, 0x60ad78ec, v141
	v_rcp_f32_e32 v189, v140
	v_lshlrev_b32_e32 v140, 16, v186
	v_lshlrev_b32_e32 v141, 16, v184
	v_add_f32_e32 v140, v136, v140
	v_add_f32_e32 v141, v132, v141
	v_mul_f32_e32 v140, 0xbfb8aa3b, v140
	v_mul_f32_e32 v141, 0xbfb8aa3b, v141
	v_exp_f32_e32 v140, v140
	v_exp_f32_e32 v141, v141
	v_pk_add_f32 v[182:183], v[182:183], 1.0 op_sel_hi:[1,0]
	v_pk_add_f32 v[190:191], v[190:191], 1.0 op_sel_hi:[1,0]
	v_pk_mul_f32 v[182:183], v[182:183], v[188:189]
	v_pk_mul_f32 v[190:191], v[190:191], v[192:193]
	v_pk_mul_f32 v[122:123], v[122:123], v[182:183]
	v_min_f32_e32 v182, 0x60ad78ec, v140
	v_min_f32_e32 v140, 0x60ad78ec, v141
	v_and_b32_e32 v141, 0xffff0000, v186
	v_add_f32_e32 v141, v137, v141
	v_mul_f32_e32 v141, 0xbfb8aa3b, v141
	v_exp_f32_e32 v141, v141
	v_and_b32_e32 v183, 0xffff0000, v184
	v_add_f32_e32 v183, v133, v183
	v_mul_f32_e32 v183, 0xbfb8aa3b, v183
	v_exp_f32_e32 v184, v183
	v_min_f32_e32 v183, 0x60ad78ec, v141
	v_lshlrev_b32_e32 v141, 16, v187
	v_add_f32_e32 v141, v138, v141
	v_add_f32_e32 v140, 1.0, v140
	v_mul_f32_e32 v141, 0xbfb8aa3b, v141
	v_rcp_f32_e32 v188, v140
	v_min_f32_e32 v140, 0x60ad78ec, v184
	v_exp_f32_e32 v141, v141
	v_lshlrev_b32_e32 v184, 16, v185
	v_add_f32_e32 v184, v134, v184
	v_mul_f32_e32 v184, 0xbfb8aa3b, v184
	v_and_b32_e32 v185, 0xffff0000, v185
	v_exp_f32_e32 v186, v184
	v_add_f32_e32 v185, v135, v185
	v_min_f32_e32 v184, 0x60ad78ec, v141
	v_and_b32_e32 v141, 0xffff0000, v187
	v_mul_f32_e32 v185, 0xbfb8aa3b, v185
	v_add_f32_e32 v141, v139, v141
	v_exp_f32_e32 v187, v185
	v_add_f32_e32 v140, 1.0, v140
	v_mul_f32_e32 v141, 0xbfb8aa3b, v141
	v_rcp_f32_e32 v189, v140
	v_min_f32_e32 v140, 0x60ad78ec, v186
	v_exp_f32_e32 v141, v141
	v_add_f32_e32 v140, 1.0, v140
	v_rcp_f32_e32 v186, v140
	v_min_f32_e32 v140, 0x60ad78ec, v187
	v_add_f32_e32 v140, 1.0, v140
	v_min_f32_e32 v185, 0x60ad78ec, v141
	v_rcp_f32_e32 v187, v140
	s_waitcnt vmcnt(10)
	v_lshlrev_b32_e32 v140, 16, v172
	v_lshlrev_b32_e32 v141, 16, v170
	v_add_f32_e32 v140, v136, v140
	v_add_f32_e32 v141, v132, v141
	v_mul_f32_e32 v140, 0xbfb8aa3b, v140
	v_mul_f32_e32 v141, 0xbfb8aa3b, v141
	v_exp_f32_e32 v140, v140
	v_exp_f32_e32 v141, v141
	v_pk_add_f32 v[182:183], v[182:183], 1.0 op_sel_hi:[1,0]
	v_and_b32_e32 v170, 0xffff0000, v170
	v_pk_mul_f32 v[182:183], v[182:183], v[188:189]
	v_add_f32_e32 v170, v133, v170
	v_pk_mul_f32 v[104:105], v[104:105], v[182:183]
	v_min_f32_e32 v182, 0x60ad78ec, v140
	v_min_f32_e32 v140, 0x60ad78ec, v141
	v_and_b32_e32 v141, 0xffff0000, v172
	v_add_f32_e32 v141, v137, v141
	v_mul_f32_e32 v141, 0xbfb8aa3b, v141
	v_exp_f32_e32 v141, v141
	v_mul_f32_e32 v170, 0xbfb8aa3b, v170
	v_exp_f32_e32 v170, v170
	v_pk_add_f32 v[184:185], v[184:185], 1.0 op_sel_hi:[1,0]
	v_min_f32_e32 v183, 0x60ad78ec, v141
	v_lshlrev_b32_e32 v141, 16, v173
	v_add_f32_e32 v141, v138, v141
	v_pk_mul_f32 v[184:185], v[184:185], v[186:187]
	v_add_f32_e32 v140, 1.0, v140
	v_mul_f32_e32 v141, 0xbfb8aa3b, v141
	v_pk_mul_f32 v[106:107], v[106:107], v[184:185]
	v_rcp_f32_e32 v184, v140
	v_min_f32_e32 v140, 0x60ad78ec, v170
	v_exp_f32_e32 v141, v141
	v_lshlrev_b32_e32 v170, 16, v171
	v_add_f32_e32 v170, v134, v170
	v_mul_f32_e32 v170, 0xbfb8aa3b, v170
	v_and_b32_e32 v171, 0xffff0000, v171
	v_exp_f32_e32 v172, v170
	v_add_f32_e32 v171, v135, v171
	v_min_f32_e32 v170, 0x60ad78ec, v141
	v_and_b32_e32 v141, 0xffff0000, v173
	v_mul_f32_e32 v171, 0xbfb8aa3b, v171
	v_add_f32_e32 v141, v139, v141
	v_exp_f32_e32 v173, v171
	v_add_f32_e32 v140, 1.0, v140
	v_mul_f32_e32 v141, 0xbfb8aa3b, v141
	v_rcp_f32_e32 v185, v140
	v_min_f32_e32 v140, 0x60ad78ec, v172
	v_exp_f32_e32 v141, v141
	v_add_f32_e32 v140, 1.0, v140
	v_rcp_f32_e32 v172, v140
	v_min_f32_e32 v140, 0x60ad78ec, v173
	v_add_f32_e32 v140, 1.0, v140
	v_min_f32_e32 v171, 0x60ad78ec, v141
	v_rcp_f32_e32 v173, v140
	s_waitcnt vmcnt(8)
	v_lshlrev_b32_e32 v140, 16, v168
	v_lshlrev_b32_e32 v141, 16, v166
	v_add_f32_e32 v140, v136, v140
	v_add_f32_e32 v141, v132, v141
	v_mul_f32_e32 v140, 0xbfb8aa3b, v140
	v_mul_f32_e32 v141, 0xbfb8aa3b, v141
	v_exp_f32_e32 v140, v140
	v_exp_f32_e32 v141, v141
	v_pk_add_f32 v[170:171], v[170:171], 1.0 op_sel_hi:[1,0]
	v_and_b32_e32 v166, 0xffff0000, v166
	v_pk_mul_f32 v[170:171], v[170:171], v[172:173]
	v_add_f32_e32 v166, v133, v166
	v_pk_mul_f32 v[90:91], v[90:91], v[170:171]
	v_min_f32_e32 v170, 0x60ad78ec, v140
	v_min_f32_e32 v140, 0x60ad78ec, v141
	v_and_b32_e32 v141, 0xffff0000, v168
	v_add_f32_e32 v141, v137, v141
	v_mul_f32_e32 v141, 0xbfb8aa3b, v141
	v_exp_f32_e32 v141, v141
	v_mul_f32_e32 v166, 0xbfb8aa3b, v166
	v_exp_f32_e32 v166, v166
	v_add_f32_e32 v140, 1.0, v140
	v_min_f32_e32 v171, 0x60ad78ec, v141
	v_lshlrev_b32_e32 v141, 16, v169
	v_add_f32_e32 v141, v138, v141
	v_mul_f32_e32 v141, 0xbfb8aa3b, v141
	v_rcp_f32_e32 v172, v140
	v_min_f32_e32 v140, 0x60ad78ec, v166
	v_exp_f32_e32 v141, v141
	v_lshlrev_b32_e32 v166, 16, v167
	v_add_f32_e32 v166, v134, v166
	v_mul_f32_e32 v166, 0xbfb8aa3b, v166
	v_and_b32_e32 v167, 0xffff0000, v167
	v_exp_f32_e32 v168, v166
	v_add_f32_e32 v167, v135, v167
	v_min_f32_e32 v166, 0x60ad78ec, v141
	v_and_b32_e32 v141, 0xffff0000, v169
	v_mul_f32_e32 v167, 0xbfb8aa3b, v167
	v_add_f32_e32 v141, v139, v141
	v_exp_f32_e32 v169, v167
	v_add_f32_e32 v140, 1.0, v140
	v_mul_f32_e32 v141, 0xbfb8aa3b, v141
	v_rcp_f32_e32 v173, v140
	v_min_f32_e32 v140, 0x60ad78ec, v168
	v_exp_f32_e32 v141, v141
	v_add_f32_e32 v140, 1.0, v140
	v_rcp_f32_e32 v168, v140
	v_min_f32_e32 v140, 0x60ad78ec, v169
	v_add_f32_e32 v140, 1.0, v140
	v_min_f32_e32 v167, 0x60ad78ec, v141
	v_rcp_f32_e32 v169, v140
	s_waitcnt vmcnt(6)
	v_lshlrev_b32_e32 v140, 16, v164
	v_lshlrev_b32_e32 v141, 16, v162
	v_add_f32_e32 v140, v136, v140
	v_add_f32_e32 v141, v132, v141
	v_mul_f32_e32 v140, 0xbfb8aa3b, v140
	v_mul_f32_e32 v141, 0xbfb8aa3b, v141
	v_exp_f32_e32 v140, v140
	v_exp_f32_e32 v141, v141
	v_pk_add_f32 v[166:167], v[166:167], 1.0 op_sel_hi:[1,0]
	v_and_b32_e32 v162, 0xffff0000, v162
	v_pk_mul_f32 v[166:167], v[166:167], v[168:169]
	v_add_f32_e32 v162, v133, v162
	v_pk_mul_f32 v[74:75], v[74:75], v[166:167]
	v_min_f32_e32 v166, 0x60ad78ec, v140
	v_min_f32_e32 v140, 0x60ad78ec, v141
	v_and_b32_e32 v141, 0xffff0000, v164
	v_add_f32_e32 v141, v137, v141
	v_mul_f32_e32 v141, 0xbfb8aa3b, v141
	v_exp_f32_e32 v141, v141
	v_mul_f32_e32 v162, 0xbfb8aa3b, v162
	v_exp_f32_e32 v162, v162
	v_add_f32_e32 v140, 1.0, v140
	v_min_f32_e32 v167, 0x60ad78ec, v141
	v_lshlrev_b32_e32 v141, 16, v165
	v_add_f32_e32 v141, v138, v141
	v_mul_f32_e32 v141, 0xbfb8aa3b, v141
	v_rcp_f32_e32 v168, v140
	v_min_f32_e32 v140, 0x60ad78ec, v162
	v_exp_f32_e32 v141, v141
	v_lshlrev_b32_e32 v162, 16, v163
	v_add_f32_e32 v162, v134, v162
	v_mul_f32_e32 v162, 0xbfb8aa3b, v162
	v_and_b32_e32 v163, 0xffff0000, v163
	v_exp_f32_e32 v164, v162
	v_add_f32_e32 v163, v135, v163
	v_min_f32_e32 v162, 0x60ad78ec, v141
	v_and_b32_e32 v141, 0xffff0000, v165
	v_mul_f32_e32 v163, 0xbfb8aa3b, v163
	v_add_f32_e32 v141, v139, v141
	v_exp_f32_e32 v165, v163
	v_add_f32_e32 v140, 1.0, v140
	v_mul_f32_e32 v141, 0xbfb8aa3b, v141
	v_rcp_f32_e32 v169, v140
	v_min_f32_e32 v140, 0x60ad78ec, v164
	v_exp_f32_e32 v141, v141
	v_add_f32_e32 v140, 1.0, v140
	v_rcp_f32_e32 v164, v140
	v_min_f32_e32 v140, 0x60ad78ec, v165
	v_add_f32_e32 v140, 1.0, v140
	v_min_f32_e32 v163, 0x60ad78ec, v141
	v_rcp_f32_e32 v165, v140
	s_waitcnt vmcnt(4)
	v_lshlrev_b32_e32 v140, 16, v160
	v_lshlrev_b32_e32 v141, 16, v158
	v_add_f32_e32 v140, v136, v140
	v_add_f32_e32 v141, v132, v141
	v_mul_f32_e32 v140, 0xbfb8aa3b, v140
	v_mul_f32_e32 v141, 0xbfb8aa3b, v141
	v_exp_f32_e32 v140, v140
	v_exp_f32_e32 v141, v141
	v_pk_add_f32 v[162:163], v[162:163], 1.0 op_sel_hi:[1,0]
	v_and_b32_e32 v158, 0xffff0000, v158
	v_pk_mul_f32 v[162:163], v[162:163], v[164:165]
	v_add_f32_e32 v158, v133, v158
	v_pk_mul_f32 v[58:59], v[58:59], v[162:163]
	v_min_f32_e32 v162, 0x60ad78ec, v140
	v_min_f32_e32 v140, 0x60ad78ec, v141
	v_and_b32_e32 v141, 0xffff0000, v160
	v_add_f32_e32 v141, v137, v141
	v_mul_f32_e32 v141, 0xbfb8aa3b, v141
	v_exp_f32_e32 v141, v141
	v_mul_f32_e32 v158, 0xbfb8aa3b, v158
	v_exp_f32_e32 v158, v158
	v_add_f32_e32 v140, 1.0, v140
	v_min_f32_e32 v163, 0x60ad78ec, v141
	v_lshlrev_b32_e32 v141, 16, v161
	v_add_f32_e32 v141, v138, v141
	v_mul_f32_e32 v141, 0xbfb8aa3b, v141
	v_rcp_f32_e32 v164, v140
	v_min_f32_e32 v140, 0x60ad78ec, v158
	v_exp_f32_e32 v141, v141
	v_lshlrev_b32_e32 v158, 16, v159
	v_add_f32_e32 v158, v134, v158
	v_mul_f32_e32 v158, 0xbfb8aa3b, v158
	v_and_b32_e32 v159, 0xffff0000, v159
	v_exp_f32_e32 v160, v158
	v_add_f32_e32 v159, v135, v159
	v_min_f32_e32 v158, 0x60ad78ec, v141
	v_and_b32_e32 v141, 0xffff0000, v161
	v_mul_f32_e32 v159, 0xbfb8aa3b, v159
	v_add_f32_e32 v141, v139, v141
	v_exp_f32_e32 v161, v159
	v_add_f32_e32 v140, 1.0, v140
	v_mul_f32_e32 v141, 0xbfb8aa3b, v141
	v_rcp_f32_e32 v165, v140
	v_min_f32_e32 v140, 0x60ad78ec, v160
	v_exp_f32_e32 v141, v141
	v_add_f32_e32 v140, 1.0, v140
	v_rcp_f32_e32 v160, v140
	v_min_f32_e32 v140, 0x60ad78ec, v161
	v_add_f32_e32 v140, 1.0, v140
	v_min_f32_e32 v159, 0x60ad78ec, v141
	v_rcp_f32_e32 v161, v140
	s_waitcnt vmcnt(2)
	v_lshlrev_b32_e32 v140, 16, v156
	v_lshlrev_b32_e32 v141, 16, v154
	v_add_f32_e32 v140, v136, v140
	v_add_f32_e32 v141, v132, v141
	v_mul_f32_e32 v140, 0xbfb8aa3b, v140
	v_mul_f32_e32 v141, 0xbfb8aa3b, v141
	v_exp_f32_e32 v140, v140
	v_exp_f32_e32 v141, v141
	v_pk_add_f32 v[158:159], v[158:159], 1.0 op_sel_hi:[1,0]
	v_and_b32_e32 v154, 0xffff0000, v154
	v_pk_mul_f32 v[158:159], v[158:159], v[160:161]
	v_add_f32_e32 v154, v133, v154
	v_pk_mul_f32 v[42:43], v[42:43], v[158:159]
	v_min_f32_e32 v158, 0x60ad78ec, v140
	v_min_f32_e32 v140, 0x60ad78ec, v141
	v_and_b32_e32 v141, 0xffff0000, v156
	v_add_f32_e32 v141, v137, v141
	v_mul_f32_e32 v141, 0xbfb8aa3b, v141
	v_exp_f32_e32 v141, v141
	v_mul_f32_e32 v154, 0xbfb8aa3b, v154
	v_exp_f32_e32 v154, v154
	v_add_f32_e32 v140, 1.0, v140
	v_min_f32_e32 v159, 0x60ad78ec, v141
	v_lshlrev_b32_e32 v141, 16, v157
	v_add_f32_e32 v141, v138, v141
	v_rcp_f32_e32 v160, v140
	v_min_f32_e32 v140, 0x60ad78ec, v154
	v_mul_f32_e32 v141, 0xbfb8aa3b, v141
	v_lshlrev_b32_e32 v154, 16, v155
	v_exp_f32_e32 v141, v141
	v_add_f32_e32 v154, v134, v154
	v_mul_f32_e32 v154, 0xbfb8aa3b, v154
	v_and_b32_e32 v155, 0xffff0000, v155
	v_exp_f32_e32 v156, v154
	v_add_f32_e32 v155, v135, v155
	v_mul_f32_e32 v155, 0xbfb8aa3b, v155
	v_min_f32_e32 v154, 0x60ad78ec, v141
	v_and_b32_e32 v141, 0xffff0000, v157
	v_exp_f32_e32 v157, v155
	v_add_f32_e32 v140, 1.0, v140
	v_rcp_f32_e32 v161, v140
	v_min_f32_e32 v140, 0x60ad78ec, v156
	v_add_f32_e32 v140, 1.0, v140
	v_rcp_f32_e32 v156, v140
	v_min_f32_e32 v140, 0x60ad78ec, v157
	v_add_f32_e32 v140, 1.0, v140
	v_rcp_f32_e32 v157, v140
	s_waitcnt vmcnt(0)
	v_lshlrev_b32_e32 v140, 16, v152
	v_add_f32_e32 v136, v136, v140
	v_lshlrev_b32_e32 v140, 16, v2
	v_add_f32_e32 v132, v132, v140
	v_mul_f32_e32 v136, 0xbfb8aa3b, v136
	v_mul_f32_e32 v132, 0xbfb8aa3b, v132
	v_exp_f32_e32 v136, v136
	v_exp_f32_e32 v140, v132
	v_and_b32_e32 v2, 0xffff0000, v2
	v_add_f32_e32 v2, v133, v2
	v_min_f32_e32 v132, 0x60ad78ec, v136
	v_min_f32_e32 v136, 0x60ad78ec, v140
	v_and_b32_e32 v140, 0xffff0000, v152
	v_add_f32_e32 v137, v137, v140
	v_mul_f32_e32 v137, 0xbfb8aa3b, v137
	v_exp_f32_e32 v137, v137
	v_add_f32_e32 v133, 1.0, v136
	v_mul_f32_e32 v2, 0xbfb8aa3b, v2
	v_rcp_f32_e32 v136, v133
	v_min_f32_e32 v133, 0x60ad78ec, v137
	v_lshlrev_b32_e32 v137, 16, v153
	v_exp_f32_e32 v2, v2
	v_add_f32_e32 v137, v138, v137
	v_mul_f32_e32 v137, 0xbfb8aa3b, v137
	v_exp_f32_e32 v138, v137
	v_lshlrev_b32_e32 v137, 16, v3
	v_and_b32_e32 v3, 0xffff0000, v3
	v_add_f32_e32 v134, v134, v137
	v_add_f32_e32 v3, v135, v3
	v_min_f32_e32 v2, 0x60ad78ec, v2
	v_mul_f32_e32 v134, 0xbfb8aa3b, v134
	v_mul_f32_e32 v3, 0xbfb8aa3b, v3
	v_exp_f32_e32 v134, v134
	v_add_f32_e32 v2, 1.0, v2
	v_exp_f32_e32 v135, v3
	v_rcp_f32_e32 v137, v2
	v_min_f32_e32 v2, 0x60ad78ec, v138
	v_and_b32_e32 v138, 0xffff0000, v153
	v_add_f32_e32 v138, v139, v138
	v_mul_f32_e32 v138, 0xbfb8aa3b, v138
	v_min_f32_e32 v134, 0x60ad78ec, v134
	v_exp_f32_e32 v138, v138
	v_min_f32_e32 v135, 0x60ad78ec, v135
	v_add_f32_e32 v141, v139, v141
	v_add_f32_e32 v3, 1.0, v134
	v_add_f32_e32 v135, 1.0, v135
	v_mul_f32_e32 v141, 0xbfb8aa3b, v141
	v_rcp_f32_e32 v134, v3
	v_rcp_f32_e32 v135, v135
	v_exp_f32_e32 v141, v141
	v_min_f32_e32 v3, 0x60ad78ec, v138
	v_pk_add_f32 v[2:3], v[2:3], 1.0 op_sel_hi:[1,0]
	v_pk_add_f32 v[132:133], v[132:133], 1.0 op_sel_hi:[1,0]
	v_pk_mul_f32 v[2:3], v[2:3], v[134:135]
	v_min_f32_e32 v155, 0x60ad78ec, v141
	v_pk_mul_f32 v[10:11], v[10:11], v[2:3]
	v_add_u32_e32 v2, s83, v0
	v_pk_add_f32 v[154:155], v[154:155], 1.0 op_sel_hi:[1,0]
	v_ashrrev_i32_e32 v3, 31, v2
	v_pk_mul_f32 v[154:155], v[154:155], v[156:157]
	v_pk_mul_f32 v[152:153], v[132:133], v[136:137]
	v_lshl_add_u64 v[136:137], v[2:3], 2, s[6:7]
	v_lshlrev_b64 v[2:3], 1, v[2:3]
	v_pk_mul_f32 v[26:27], v[26:27], v[154:155]
	v_mad_i64_i32 v[154:155], vcc, v174, s2, v[2:3]
	v_lshl_add_u64 v[154:155], s[30:31], 0, v[154:155]
	v_add_co_u32_e32 v156, vcc, s76, v154
	v_pk_add_f32 v[182:183], v[182:183], 1.0 op_sel_hi:[1,0]
	s_nop 0
	v_addc_co_u32_e32 v157, vcc, 0, v155, vcc
	v_add_co_u32_e32 v154, vcc, s77, v154
	v_pk_mul_f32 v[182:183], v[182:183], v[184:185]
	s_nop 0
	v_addc_co_u32_e32 v155, vcc, 0, v155, vcc
	v_pk_mul_f32 v[88:89], v[88:89], v[182:183]
	v_pk_add_f32 v[158:159], v[158:159], 1.0 op_sel_hi:[1,0]
	global_load_dwordx4 v[132:135], v[136:137], off offset:-4096
	s_nop 0
	global_load_dwordx4 v[136:139], v[136:137], off
	v_pk_mul_f32 v[158:159], v[158:159], v[160:161]
	global_load_dwordx2 v[182:183], v[154:155], off offset:1024
	v_mad_i64_i32 v[154:155], vcc, v175, s2, v[2:3]
	v_lshl_add_u64 v[154:155], s[30:31], 0, v[154:155]
	v_pk_mul_f32 v[24:25], v[24:25], v[158:159]
	v_add_co_u32_e32 v158, vcc, s76, v154
	v_pk_mul_f32 v[8:9], v[8:9], v[152:153]
	s_nop 0
	v_addc_co_u32_e32 v159, vcc, 0, v155, vcc
	v_add_co_u32_e32 v154, vcc, s77, v154
	v_pk_add_f32 v[170:171], v[170:171], 1.0 op_sel_hi:[1,0]
	s_nop 0
	v_addc_co_u32_e32 v155, vcc, 0, v155, vcc
	global_load_dwordx2 v[174:175], v[158:159], off offset:3072
	global_load_dwordx2 v[184:185], v[154:155], off offset:1024
	global_load_dwordx2 v[186:187], v[156:157], off offset:3072
	v_mad_i64_i32 v[152:153], vcc, v176, s2, v[2:3]
	v_lshl_add_u64 v[152:153], s[30:31], 0, v[152:153]
	v_add_co_u32_e32 v154, vcc, s76, v152
	v_pk_add_f32 v[166:167], v[166:167], 1.0 op_sel_hi:[1,0]
	s_nop 0
	v_addc_co_u32_e32 v155, vcc, 0, v153, vcc
	v_add_co_u32_e32 v152, vcc, s77, v152
	v_pk_mul_f32 v[170:171], v[170:171], v[172:173]
	s_nop 0
	v_addc_co_u32_e32 v153, vcc, 0, v153, vcc
	v_mad_i64_i32 v[156:157], vcc, v177, s2, v[2:3]
	v_lshl_add_u64 v[156:157], s[30:31], 0, v[156:157]
	v_add_co_u32_e32 v158, vcc, s76, v156
	v_pk_mul_f32 v[166:167], v[166:167], v[168:169]
	s_nop 0
	v_addc_co_u32_e32 v159, vcc, 0, v157, vcc
	v_add_co_u32_e32 v156, vcc, s77, v156
	v_pk_mul_f32 v[72:73], v[72:73], v[170:171]
	v_pk_mul_f32 v[56:57], v[56:57], v[166:167]
	v_addc_co_u32_e32 v157, vcc, 0, v157, vcc
	global_load_dwordx2 v[170:171], v[154:155], off offset:3072
	global_load_dwordx2 v[172:173], v[152:153], off offset:1024
	global_load_dwordx2 v[166:167], v[158:159], off offset:3072
	global_load_dwordx2 v[168:169], v[156:157], off offset:1024
	v_mad_i64_i32 v[152:153], vcc, v178, s2, v[2:3]
	v_lshl_add_u64 v[152:153], s[30:31], 0, v[152:153]
	v_add_co_u32_e32 v154, vcc, s76, v152
	v_pk_add_f32 v[162:163], v[162:163], 1.0 op_sel_hi:[1,0]
	s_nop 0
	v_addc_co_u32_e32 v155, vcc, 0, v153, vcc
	v_add_co_u32_e32 v152, vcc, s77, v152
	v_pk_mul_f32 v[162:163], v[162:163], v[164:165]
	s_nop 0
	v_addc_co_u32_e32 v153, vcc, 0, v153, vcc
	v_mad_i64_i32 v[156:157], vcc, v179, s2, v[2:3]
	v_lshl_add_u64 v[156:157], s[30:31], 0, v[156:157]
	v_add_co_u32_e32 v158, vcc, s76, v156
	v_pk_mul_f32 v[40:41], v[40:41], v[162:163]
	s_nop 0
	v_addc_co_u32_e32 v159, vcc, 0, v157, vcc
	v_add_co_u32_e32 v156, vcc, s77, v156
	v_pk_mul_f32 v[120:121], v[120:121], v[190:191]
	s_nop 0
	v_addc_co_u32_e32 v157, vcc, 0, v157, vcc
	global_load_dwordx2 v[162:163], v[154:155], off offset:3072
	global_load_dwordx2 v[164:165], v[152:153], off offset:1024
	s_nop 0
	global_load_dwordx2 v[158:159], v[158:159], off offset:3072
	s_nop 0
	global_load_dwordx2 v[160:161], v[156:157], off offset:1024
	v_mad_i64_i32 v[152:153], vcc, v180, s2, v[2:3]
	v_lshl_add_u64 v[152:153], s[30:31], 0, v[152:153]
	v_add_co_u32_e32 v154, vcc, s76, v152
	s_waitcnt vmcnt(11)
	v_lshlrev_b32_e32 v0, 16, v182
	v_addc_co_u32_e32 v155, vcc, 0, v153, vcc
	v_add_co_u32_e32 v152, vcc, s77, v152
	v_add_f32_e32 v0, v136, v0
	s_nop 0
	v_addc_co_u32_e32 v153, vcc, 0, v153, vcc
	v_mad_i64_i32 v[2:3], vcc, v181, s2, v[2:3]
	v_lshl_add_u64 v[2:3], s[30:31], 0, v[2:3]
	v_add_co_u32_e32 v176, vcc, s76, v2
	v_mul_f32_e32 v0, 0xbfb8aa3b, v0
	s_nop 0
	v_addc_co_u32_e32 v177, vcc, 0, v3, vcc
	v_add_co_u32_e32 v178, vcc, s77, v2
	s_waitcnt vmcnt(8)
	v_lshlrev_b32_e32 v2, 16, v186
	v_add_f32_e32 v2, v132, v2
	v_mul_f32_e32 v2, 0xbfb8aa3b, v2
	v_exp_f32_e32 v0, v0
	v_exp_f32_e32 v140, v2
	v_and_b32_e32 v141, 0xffff0000, v186
	v_add_f32_e32 v141, v133, v141
	v_addc_co_u32_e32 v179, vcc, 0, v3, vcc
	global_load_dwordx2 v[154:155], v[154:155], off offset:3072
	s_nop 0
	global_load_dwordx2 v[156:157], v[152:153], off offset:1024
	global_load_dwordx2 v[2:3], v[176:177], off offset:3072
	s_nop 0
	global_load_dwordx2 v[152:153], v[178:179], off offset:1024
	v_min_f32_e32 v176, 0x60ad78ec, v0
	v_min_f32_e32 v0, 0x60ad78ec, v140
	v_and_b32_e32 v140, 0xffff0000, v182
	v_mul_f32_e32 v141, 0xbfb8aa3b, v141
	v_add_f32_e32 v140, v137, v140
	v_exp_f32_e32 v141, v141
	v_mul_f32_e32 v140, 0xbfb8aa3b, v140
	v_exp_f32_e32 v140, v140
	v_add_f32_e32 v0, 1.0, v0
	v_rcp_f32_e32 v178, v0
	v_min_f32_e32 v0, 0x60ad78ec, v141
	v_lshlrev_b32_e32 v141, 16, v187
	v_add_f32_e32 v141, v134, v141
	v_min_f32_e32 v177, 0x60ad78ec, v140
	v_lshlrev_b32_e32 v140, 16, v183
	v_mul_f32_e32 v141, 0xbfb8aa3b, v141
	v_add_f32_e32 v140, v138, v140
	v_exp_f32_e32 v141, v141
	v_mul_f32_e32 v140, 0xbfb8aa3b, v140
	v_exp_f32_e32 v140, v140
	v_add_f32_e32 v0, 1.0, v0
	v_rcp_f32_e32 v179, v0
	v_min_f32_e32 v0, 0x60ad78ec, v141
	v_and_b32_e32 v141, 0xffff0000, v187
	v_add_f32_e32 v141, v135, v141
	v_min_f32_e32 v180, 0x60ad78ec, v140
	v_and_b32_e32 v140, 0xffff0000, v183
	v_mul_f32_e32 v141, 0xbfb8aa3b, v141
	v_add_f32_e32 v140, v139, v140
	v_exp_f32_e32 v141, v141
	v_mul_f32_e32 v140, 0xbfb8aa3b, v140
	v_exp_f32_e32 v140, v140
	v_add_f32_e32 v0, 1.0, v0
	v_rcp_f32_e32 v182, v0
	v_min_f32_e32 v0, 0x60ad78ec, v141
	v_add_f32_e32 v0, 1.0, v0
	v_min_f32_e32 v181, 0x60ad78ec, v140
	v_rcp_f32_e32 v183, v0
	v_lshlrev_b32_e32 v0, 16, v184
	v_lshlrev_b32_e32 v140, 16, v174
	v_add_f32_e32 v0, v136, v0
	v_add_f32_e32 v140, v132, v140
	v_mul_f32_e32 v0, 0xbfb8aa3b, v0
	v_mul_f32_e32 v140, 0xbfb8aa3b, v140
	v_exp_f32_e32 v0, v0
	v_exp_f32_e32 v140, v140
	v_pk_add_f32 v[176:177], v[176:177], 1.0 op_sel_hi:[1,0]
	v_and_b32_e32 v141, 0xffff0000, v174
	v_pk_mul_f32 v[176:177], v[176:177], v[178:179]
	v_add_f32_e32 v141, v133, v141
	v_pk_mul_f32 v[116:117], v[116:117], v[176:177]
	v_min_f32_e32 v176, 0x60ad78ec, v0
	v_min_f32_e32 v0, 0x60ad78ec, v140
	v_and_b32_e32 v140, 0xffff0000, v184
	v_mul_f32_e32 v141, 0xbfb8aa3b, v141
	v_add_f32_e32 v140, v137, v140
	v_exp_f32_e32 v141, v141
	v_mul_f32_e32 v140, 0xbfb8aa3b, v140
	v_pk_add_f32 v[180:181], v[180:181], 1.0 op_sel_hi:[1,0]
	v_exp_f32_e32 v140, v140
	v_pk_mul_f32 v[178:179], v[180:181], v[182:183]
	v_add_f32_e32 v0, 1.0, v0
	v_pk_mul_f32 v[118:119], v[118:119], v[178:179]
	v_rcp_f32_e32 v178, v0
	v_min_f32_e32 v0, 0x60ad78ec, v141
	v_lshlrev_b32_e32 v141, 16, v175
	v_add_f32_e32 v141, v134, v141
	v_min_f32_e32 v177, 0x60ad78ec, v140
	v_lshlrev_b32_e32 v140, 16, v185
	v_mul_f32_e32 v141, 0xbfb8aa3b, v141
	v_add_f32_e32 v140, v138, v140
	v_exp_f32_e32 v141, v141
	v_mul_f32_e32 v140, 0xbfb8aa3b, v140
	v_exp_f32_e32 v140, v140
	v_add_f32_e32 v0, 1.0, v0
	v_rcp_f32_e32 v179, v0
	v_min_f32_e32 v0, 0x60ad78ec, v141
	v_and_b32_e32 v141, 0xffff0000, v175
	v_add_f32_e32 v141, v135, v141
	v_min_f32_e32 v174, 0x60ad78ec, v140
	v_and_b32_e32 v140, 0xffff0000, v185
	v_mul_f32_e32 v141, 0xbfb8aa3b, v141
	v_add_f32_e32 v140, v139, v140
	v_exp_f32_e32 v141, v141
	v_mul_f32_e32 v140, 0xbfb8aa3b, v140
	v_exp_f32_e32 v140, v140
	v_add_f32_e32 v0, 1.0, v0
	v_rcp_f32_e32 v180, v0
	v_min_f32_e32 v0, 0x60ad78ec, v141
	v_add_f32_e32 v0, 1.0, v0
	v_min_f32_e32 v175, 0x60ad78ec, v140
	v_rcp_f32_e32 v181, v0
	s_waitcnt vmcnt(10)
	v_lshlrev_b32_e32 v0, 16, v172
	v_lshlrev_b32_e32 v140, 16, v170
	v_add_f32_e32 v0, v136, v0
	v_add_f32_e32 v140, v132, v140
	v_mul_f32_e32 v0, 0xbfb8aa3b, v0
	v_mul_f32_e32 v140, 0xbfb8aa3b, v140
	v_exp_f32_e32 v0, v0
	v_exp_f32_e32 v140, v140
	v_pk_add_f32 v[174:175], v[174:175], 1.0 op_sel_hi:[1,0]
	v_and_b32_e32 v141, 0xffff0000, v170
	v_pk_mul_f32 v[174:175], v[174:175], v[180:181]
	v_add_f32_e32 v141, v133, v141
	v_pk_mul_f32 v[102:103], v[102:103], v[174:175]
	v_min_f32_e32 v174, 0x60ad78ec, v0
	v_min_f32_e32 v0, 0x60ad78ec, v140
	v_and_b32_e32 v140, 0xffff0000, v172
	v_mul_f32_e32 v141, 0xbfb8aa3b, v141
	v_add_f32_e32 v140, v137, v140
	v_exp_f32_e32 v141, v141
	v_mul_f32_e32 v140, 0xbfb8aa3b, v140
	v_pk_add_f32 v[176:177], v[176:177], 1.0 op_sel_hi:[1,0]
	v_exp_f32_e32 v140, v140
	v_pk_mul_f32 v[176:177], v[176:177], v[178:179]
	v_add_f32_e32 v0, 1.0, v0
	v_pk_mul_f32 v[100:101], v[100:101], v[176:177]
	v_rcp_f32_e32 v176, v0
	v_min_f32_e32 v0, 0x60ad78ec, v141
	v_lshlrev_b32_e32 v141, 16, v171
	v_add_f32_e32 v141, v134, v141
	v_min_f32_e32 v175, 0x60ad78ec, v140
	v_lshlrev_b32_e32 v140, 16, v173
	v_mul_f32_e32 v141, 0xbfb8aa3b, v141
	v_add_f32_e32 v140, v138, v140
	v_exp_f32_e32 v141, v141
	v_mul_f32_e32 v140, 0xbfb8aa3b, v140
	v_exp_f32_e32 v140, v140
	v_add_f32_e32 v0, 1.0, v0
	v_rcp_f32_e32 v177, v0
	v_min_f32_e32 v0, 0x60ad78ec, v141
	v_and_b32_e32 v141, 0xffff0000, v171
	v_add_f32_e32 v141, v135, v141
	v_min_f32_e32 v170, 0x60ad78ec, v140
	v_and_b32_e32 v140, 0xffff0000, v173
	v_mul_f32_e32 v141, 0xbfb8aa3b, v141
	v_add_f32_e32 v140, v139, v140
	v_exp_f32_e32 v141, v141
	v_mul_f32_e32 v140, 0xbfb8aa3b, v140
	v_exp_f32_e32 v140, v140
	v_add_f32_e32 v0, 1.0, v0
	v_rcp_f32_e32 v172, v0
	v_min_f32_e32 v0, 0x60ad78ec, v141
	v_add_f32_e32 v0, 1.0, v0
	v_min_f32_e32 v171, 0x60ad78ec, v140
	v_rcp_f32_e32 v173, v0
	s_waitcnt vmcnt(8)
	v_lshlrev_b32_e32 v0, 16, v168
	v_lshlrev_b32_e32 v140, 16, v166
	v_add_f32_e32 v0, v136, v0
	v_add_f32_e32 v140, v132, v140
	v_mul_f32_e32 v0, 0xbfb8aa3b, v0
	v_mul_f32_e32 v140, 0xbfb8aa3b, v140
	v_exp_f32_e32 v0, v0
	v_exp_f32_e32 v140, v140
	v_pk_add_f32 v[170:171], v[170:171], 1.0 op_sel_hi:[1,0]
	v_and_b32_e32 v141, 0xffff0000, v166
	v_pk_mul_f32 v[170:171], v[170:171], v[172:173]
	v_add_f32_e32 v141, v133, v141
	v_pk_mul_f32 v[86:87], v[86:87], v[170:171]
	v_min_f32_e32 v170, 0x60ad78ec, v0
	v_min_f32_e32 v0, 0x60ad78ec, v140
	v_and_b32_e32 v140, 0xffff0000, v168
	v_mul_f32_e32 v141, 0xbfb8aa3b, v141
	v_add_f32_e32 v140, v137, v140
	v_exp_f32_e32 v141, v141
	v_mul_f32_e32 v140, 0xbfb8aa3b, v140
	v_exp_f32_e32 v140, v140
	v_add_f32_e32 v0, 1.0, v0
	v_rcp_f32_e32 v172, v0
	v_min_f32_e32 v0, 0x60ad78ec, v141
	v_lshlrev_b32_e32 v141, 16, v167
	v_add_f32_e32 v141, v134, v141
	v_min_f32_e32 v171, 0x60ad78ec, v140
	v_lshlrev_b32_e32 v140, 16, v169
	v_mul_f32_e32 v141, 0xbfb8aa3b, v141
	v_add_f32_e32 v140, v138, v140
	v_exp_f32_e32 v141, v141
	v_mul_f32_e32 v140, 0xbfb8aa3b, v140
	v_exp_f32_e32 v140, v140
	v_add_f32_e32 v0, 1.0, v0
	v_rcp_f32_e32 v173, v0
	v_min_f32_e32 v0, 0x60ad78ec, v141
	v_and_b32_e32 v141, 0xffff0000, v167
	v_add_f32_e32 v141, v135, v141
	v_min_f32_e32 v166, 0x60ad78ec, v140
	v_and_b32_e32 v140, 0xffff0000, v169
	v_mul_f32_e32 v141, 0xbfb8aa3b, v141
	v_add_f32_e32 v140, v139, v140
	v_exp_f32_e32 v141, v141
	v_mul_f32_e32 v140, 0xbfb8aa3b, v140
	v_exp_f32_e32 v140, v140
	v_add_f32_e32 v0, 1.0, v0
	v_rcp_f32_e32 v168, v0
	v_min_f32_e32 v0, 0x60ad78ec, v141
	v_add_f32_e32 v0, 1.0, v0
	v_min_f32_e32 v167, 0x60ad78ec, v140
	v_rcp_f32_e32 v169, v0
	s_waitcnt vmcnt(6)
	v_lshlrev_b32_e32 v0, 16, v164
	v_lshlrev_b32_e32 v140, 16, v162
	v_add_f32_e32 v0, v136, v0
	v_add_f32_e32 v140, v132, v140
	v_mul_f32_e32 v0, 0xbfb8aa3b, v0
	v_mul_f32_e32 v140, 0xbfb8aa3b, v140
	v_exp_f32_e32 v0, v0
	v_exp_f32_e32 v140, v140
	v_pk_add_f32 v[166:167], v[166:167], 1.0 op_sel_hi:[1,0]
	v_and_b32_e32 v141, 0xffff0000, v162
	v_pk_mul_f32 v[166:167], v[166:167], v[168:169]
	v_add_f32_e32 v141, v133, v141
	v_pk_mul_f32 v[70:71], v[70:71], v[166:167]
	v_min_f32_e32 v166, 0x60ad78ec, v0
	v_min_f32_e32 v0, 0x60ad78ec, v140
	v_and_b32_e32 v140, 0xffff0000, v164
	v_mul_f32_e32 v141, 0xbfb8aa3b, v141
	v_add_f32_e32 v140, v137, v140
	v_exp_f32_e32 v141, v141
	v_mul_f32_e32 v140, 0xbfb8aa3b, v140
	v_exp_f32_e32 v140, v140
	v_add_f32_e32 v0, 1.0, v0
	v_rcp_f32_e32 v168, v0
	v_min_f32_e32 v0, 0x60ad78ec, v141
	v_lshlrev_b32_e32 v141, 16, v163
	v_add_f32_e32 v141, v134, v141
	v_min_f32_e32 v167, 0x60ad78ec, v140
	v_lshlrev_b32_e32 v140, 16, v165
	v_mul_f32_e32 v141, 0xbfb8aa3b, v141
	v_add_f32_e32 v140, v138, v140
	v_exp_f32_e32 v141, v141
	v_mul_f32_e32 v140, 0xbfb8aa3b, v140
	v_exp_f32_e32 v140, v140
	v_add_f32_e32 v0, 1.0, v0
	v_rcp_f32_e32 v169, v0
	v_min_f32_e32 v0, 0x60ad78ec, v141
	v_and_b32_e32 v141, 0xffff0000, v163
	v_add_f32_e32 v141, v135, v141
	v_min_f32_e32 v162, 0x60ad78ec, v140
	v_and_b32_e32 v140, 0xffff0000, v165
	v_mul_f32_e32 v141, 0xbfb8aa3b, v141
	v_add_f32_e32 v140, v139, v140
	v_exp_f32_e32 v141, v141
	v_mul_f32_e32 v140, 0xbfb8aa3b, v140
	v_exp_f32_e32 v140, v140
	v_add_f32_e32 v0, 1.0, v0
	v_rcp_f32_e32 v164, v0
	v_min_f32_e32 v0, 0x60ad78ec, v141
	v_add_f32_e32 v0, 1.0, v0
	v_min_f32_e32 v163, 0x60ad78ec, v140
	v_rcp_f32_e32 v165, v0
	s_waitcnt vmcnt(4)
	v_lshlrev_b32_e32 v0, 16, v160
	v_lshlrev_b32_e32 v140, 16, v158
	v_add_f32_e32 v0, v136, v0
	v_add_f32_e32 v140, v132, v140
	v_mul_f32_e32 v0, 0xbfb8aa3b, v0
	v_mul_f32_e32 v140, 0xbfb8aa3b, v140
	v_exp_f32_e32 v0, v0
	v_exp_f32_e32 v140, v140
	v_pk_add_f32 v[162:163], v[162:163], 1.0 op_sel_hi:[1,0]
	v_and_b32_e32 v141, 0xffff0000, v158
	v_pk_mul_f32 v[162:163], v[162:163], v[164:165]
	v_add_f32_e32 v141, v133, v141
	v_pk_mul_f32 v[54:55], v[54:55], v[162:163]
	v_min_f32_e32 v162, 0x60ad78ec, v0
	v_min_f32_e32 v0, 0x60ad78ec, v140
	v_and_b32_e32 v140, 0xffff0000, v160
	v_mul_f32_e32 v141, 0xbfb8aa3b, v141
	v_add_f32_e32 v140, v137, v140
	v_exp_f32_e32 v141, v141
	v_mul_f32_e32 v140, 0xbfb8aa3b, v140
	v_exp_f32_e32 v140, v140
	v_add_f32_e32 v0, 1.0, v0
	v_rcp_f32_e32 v164, v0
	v_min_f32_e32 v0, 0x60ad78ec, v141
	v_lshlrev_b32_e32 v141, 16, v159
	v_add_f32_e32 v141, v134, v141
	v_min_f32_e32 v163, 0x60ad78ec, v140
	v_lshlrev_b32_e32 v140, 16, v161
	v_mul_f32_e32 v141, 0xbfb8aa3b, v141
	v_add_f32_e32 v140, v138, v140
	v_exp_f32_e32 v141, v141
	v_mul_f32_e32 v140, 0xbfb8aa3b, v140
	v_exp_f32_e32 v140, v140
	v_add_f32_e32 v0, 1.0, v0
	v_rcp_f32_e32 v165, v0
	v_min_f32_e32 v0, 0x60ad78ec, v141
	v_and_b32_e32 v141, 0xffff0000, v159
	v_add_f32_e32 v141, v135, v141
	v_min_f32_e32 v158, 0x60ad78ec, v140
	v_and_b32_e32 v140, 0xffff0000, v161
	v_mul_f32_e32 v141, 0xbfb8aa3b, v141
	v_add_f32_e32 v140, v139, v140
	v_exp_f32_e32 v141, v141
	v_mul_f32_e32 v140, 0xbfb8aa3b, v140
	v_exp_f32_e32 v140, v140
	v_add_f32_e32 v0, 1.0, v0
	v_rcp_f32_e32 v160, v0
	v_min_f32_e32 v0, 0x60ad78ec, v141
	v_add_f32_e32 v0, 1.0, v0
	v_min_f32_e32 v159, 0x60ad78ec, v140
	v_rcp_f32_e32 v161, v0
	s_waitcnt vmcnt(2)
	v_lshlrev_b32_e32 v0, 16, v156
	v_lshlrev_b32_e32 v140, 16, v154
	v_add_f32_e32 v0, v136, v0
	v_add_f32_e32 v140, v132, v140
	v_mul_f32_e32 v0, 0xbfb8aa3b, v0
	v_mul_f32_e32 v140, 0xbfb8aa3b, v140
	v_and_b32_e32 v141, 0xffff0000, v154
	v_exp_f32_e32 v0, v0
	v_exp_f32_e32 v140, v140
	v_add_f32_e32 v141, v133, v141
	v_mul_f32_e32 v141, 0xbfb8aa3b, v141
	v_pk_add_f32 v[158:159], v[158:159], 1.0 op_sel_hi:[1,0]
	v_exp_f32_e32 v141, v141
	v_pk_mul_f32 v[158:159], v[158:159], v[160:161]
	v_pk_add_f32 v[174:175], v[174:175], 1.0 op_sel_hi:[1,0]
	v_pk_mul_f32 v[38:39], v[38:39], v[158:159]
	v_min_f32_e32 v158, 0x60ad78ec, v0
	v_min_f32_e32 v0, 0x60ad78ec, v140
	v_add_f32_e32 v0, 1.0, v0
	v_rcp_f32_e32 v160, v0
	v_min_f32_e32 v0, 0x60ad78ec, v141
	v_lshlrev_b32_e32 v141, 16, v155
	v_add_f32_e32 v141, v134, v141
	v_and_b32_e32 v140, 0xffff0000, v156
	v_mul_f32_e32 v141, 0xbfb8aa3b, v141
	v_add_f32_e32 v140, v137, v140
	v_exp_f32_e32 v141, v141
	v_mul_f32_e32 v140, 0xbfb8aa3b, v140
	v_exp_f32_e32 v140, v140
	v_add_f32_e32 v0, 1.0, v0
	v_rcp_f32_e32 v161, v0
	v_min_f32_e32 v0, 0x60ad78ec, v141
	v_and_b32_e32 v141, 0xffff0000, v155
	v_add_f32_e32 v141, v135, v141
	v_min_f32_e32 v159, 0x60ad78ec, v140
	v_lshlrev_b32_e32 v140, 16, v157
	v_mul_f32_e32 v141, 0xbfb8aa3b, v141
	v_add_f32_e32 v140, v138, v140
	v_exp_f32_e32 v141, v141
	v_mul_f32_e32 v140, 0xbfb8aa3b, v140
	v_exp_f32_e32 v140, v140
	v_add_f32_e32 v0, 1.0, v0
	v_rcp_f32_e32 v156, v0
	v_min_f32_e32 v0, 0x60ad78ec, v141
	v_add_f32_e32 v0, 1.0, v0
	v_min_f32_e32 v154, 0x60ad78ec, v140
	v_and_b32_e32 v140, 0xffff0000, v157
	v_rcp_f32_e32 v157, v0
	s_waitcnt vmcnt(0)
	v_lshlrev_b32_e32 v0, 16, v152
	v_add_f32_e32 v0, v136, v0
	v_lshlrev_b32_e32 v136, 16, v2
	v_add_f32_e32 v132, v132, v136
	v_mul_f32_e32 v0, 0xbfb8aa3b, v0
	v_mul_f32_e32 v132, 0xbfb8aa3b, v132
	v_exp_f32_e32 v0, v0
	v_exp_f32_e32 v136, v132
	v_and_b32_e32 v2, 0xffff0000, v2
	v_add_f32_e32 v2, v133, v2
	v_min_f32_e32 v132, 0x60ad78ec, v0
	v_min_f32_e32 v0, 0x60ad78ec, v136
	v_and_b32_e32 v136, 0xffff0000, v152
	v_add_f32_e32 v136, v137, v136
	v_mul_f32_e32 v136, 0xbfb8aa3b, v136
	v_exp_f32_e32 v137, v136
	v_mul_f32_e32 v2, 0xbfb8aa3b, v2
	v_exp_f32_e32 v2, v2
	v_add_f32_e32 v0, 1.0, v0
	v_min_f32_e32 v133, 0x60ad78ec, v137
	v_lshlrev_b32_e32 v137, 16, v3
	v_add_f32_e32 v134, v134, v137
	v_mul_f32_e32 v134, 0xbfb8aa3b, v134
	v_exp_f32_e32 v134, v134
	v_and_b32_e32 v3, 0xffff0000, v3
	v_add_f32_e32 v3, v135, v3
	v_rcp_f32_e32 v136, v0
	v_min_f32_e32 v0, 0x60ad78ec, v2
	v_mul_f32_e32 v3, 0xbfb8aa3b, v3
	v_add_f32_e32 v0, 1.0, v0
	v_exp_f32_e32 v135, v3
	v_lshlrev_b32_e32 v2, 16, v153
	v_rcp_f32_e32 v137, v0
	v_min_f32_e32 v0, 0x60ad78ec, v134
	v_and_b32_e32 v134, 0xffff0000, v153
	v_add_f32_e32 v140, v139, v140
	v_add_f32_e32 v2, v138, v2
	v_add_f32_e32 v134, v139, v134
	v_mul_f32_e32 v140, 0xbfb8aa3b, v140
	v_mul_f32_e32 v2, 0xbfb8aa3b, v2
	v_mul_f32_e32 v134, 0xbfb8aa3b, v134
	v_add_f32_e32 v0, 1.0, v0
	v_exp_f32_e32 v140, v140
	v_exp_f32_e32 v2, v2
	v_exp_f32_e32 v138, v134
	v_rcp_f32_e32 v134, v0
	v_min_f32_e32 v0, 0x60ad78ec, v135
	v_add_f32_e32 v0, 1.0, v0
	v_rcp_f32_e32 v135, v0
	v_min_f32_e32 v155, 0x60ad78ec, v140
	v_min_f32_e32 v2, 0x60ad78ec, v2
	v_min_f32_e32 v3, 0x60ad78ec, v138
	v_pk_add_f32 v[170:171], v[170:171], 1.0 op_sel_hi:[1,0]
	v_pk_add_f32 v[166:167], v[166:167], 1.0 op_sel_hi:[1,0]
	v_pk_add_f32 v[162:163], v[162:163], 1.0 op_sel_hi:[1,0]
	v_pk_add_f32 v[154:155], v[154:155], 1.0 op_sel_hi:[1,0]
	v_pk_add_f32 v[158:159], v[158:159], 1.0 op_sel_hi:[1,0]
	v_pk_add_f32 v[2:3], v[2:3], 1.0 op_sel_hi:[1,0]
	v_pk_add_f32 v[132:133], v[132:133], 1.0 op_sel_hi:[1,0]
	v_pk_mul_f32 v[174:175], v[174:175], v[176:177]
	v_pk_mul_f32 v[170:171], v[170:171], v[172:173]
	v_pk_mul_f32 v[166:167], v[166:167], v[168:169]
	v_pk_mul_f32 v[162:163], v[162:163], v[164:165]
	v_pk_mul_f32 v[158:159], v[158:159], v[160:161]
	v_pk_mul_f32 v[154:155], v[154:155], v[156:157]
	v_pk_mul_f32 v[132:133], v[132:133], v[136:137]
	v_pk_mul_f32 v[2:3], v[2:3], v[134:135]
	v_pk_mul_f32 v[84:85], v[84:85], v[174:175]
	v_pk_mul_f32 v[68:69], v[68:69], v[170:171]
	v_pk_mul_f32 v[52:53], v[52:53], v[166:167]
	v_pk_mul_f32 v[36:37], v[36:37], v[162:163]
	v_pk_mul_f32 v[22:23], v[22:23], v[154:155]
	v_pk_mul_f32 v[20:21], v[20:21], v[158:159]
	v_pk_mul_f32 v[6:7], v[6:7], v[2:3]
	v_pk_mul_f32 v[4:5], v[4:5], v[132:133]
